# residual epilogues (out/down GEMMs, 3 of 4): 16 serial load-wait-store pieces -> 8 loads per half hoisted into dead fragment VGPRs, one wait; plus conv tail fast path, no grid.sync, converter loads ba
# speedup vs baseline: 1.0075x; 1.0075x over previous
.LBB0_436:
	v_mov_b32_e32 v0, v183
	s_mul_i32 s94, s22, 0x180
	v_ashrrev_i32_e32 v1, 6, v0
	v_cmp_lt_i32_e32 vcc, 1, v1
	s_and_saveexec_b64 s[4:5], vcc
	s_xor_b64 s[4:5], exec, s[4:5]
	s_cbranch_execz .LBB0_456
	s_mul_i32 s6, s20, 0x180
	s_addk_i32 s6, 0xff80
	v_add_u32_e32 v36, s6, v0
	s_mov_b32 s6, 0x104000
	v_cmp_gt_i32_e32 vcc, s6, v36
	v_lshlrev_b32_e32 v37, 3, v36
	s_and_saveexec_b64 s[6:7], vcc
	s_cbranch_execz .LBB0_452
	s_add_u32 s8, s0, 0x18cc0000
	s_addc_u32 s9, s1, 0
	s_add_u32 s10, s0, 0x19d40000
	s_addc_u32 s11, s1, 0
	s_add_u32 s12, s0, 0x24240000
	s_addc_u32 s13, s1, 0
	s_add_u32 s76, s68, 0x4390000
	s_addc_u32 s77, s69, 0
	s_add_u32 s78, s68, 0x4300000
	s_addc_u32 s79, s69, 0
	v_lshlrev_b32_e32 v38, 3, v36
	s_mov_b64 s[80:81], 0
	v_mov_b32_e32 v31, 0
	s_mov_b64 s[82:83], 0x1000
	v_mov_b32_e32 v39, v36
	s_movk_i32 s21, 0x7fd
	v_readlane_b32 s42, v254, 36
	v_readlane_b32 s43, v254, 37
	s_nop 4
	v_and_b32_e32 v65, 0x3f8, v38
	v_lshlrev_b32_e32 v64, 1, v65
	v_lshlrev_b32_e32 v65, 2, v65
	s_add_u32 s36, s42, 0x1000
	s_addc_u32 s37, s43, 0
	s_add_u32 s38, s42, 0x2000
	s_addc_u32 s39, s43, 0
	global_load_dwordx4 v[68:71], v65, s[42:43]
	global_load_dwordx4 v[72:75], v65, s[42:43] offset:16
	global_load_dwordx4 v[76:79], v65, s[36:37]
	global_load_dwordx4 v[80:83], v65, s[36:37] offset:16
	global_load_dwordx4 v[84:87], v65, s[38:39]
	global_load_dwordx4 v[88:91], v65, s[38:39] offset:16
	s_waitcnt vmcnt(0)
	s_branch .LBB0_440

.LBB0_440:
	v_readfirstlane_b32 s24, v39
	s_nop 0
	s_ashr_i32 s25, s24, 7
	s_cmpk_gt_i32 s25, 0x1fff
	s_cbranch_scc1 .Lconv_slow_L0
	s_and_b32 s26, s25, 0x7ff
	s_add_i32 s26, s26, -2
	s_cmpk_gt_u32 s26, 0x7fb
	s_cbranch_scc1 .Lconv_slow_L0
	s_lshl_b32 s25, s25, 11
	s_add_u32 s36, s10, s25
	s_addc_u32 s37, s11, 0
	s_add_u32 s38, s8, s25
	s_addc_u32 s39, s9, 0
	s_add_u32 s40, s12, s25
	s_addc_u32 s41, s13, 0
	global_load_dwordx4 v[92:95], v64, s[38:39]
	global_load_dwordx4 v[96:99], v64, s[36:37]
	global_load_dwordx4 v[100:103], v64, s[36:37] offset:-2048
	global_load_dwordx4 v[104:107], v64, s[36:37] offset:-4096
	s_mul_i32 s26, s22, 0xc00
	v_add_u32_e32 v39, s94, v39
	v_add_u32_e32 v38, s26, v38
	s_add_i32 s24, s24, s94
	s_waitcnt vmcnt(0)
	v_lshlrev_b32_e32 v116, 16, v100
	v_and_b32_e32 v117, 0xffff0000, v100
	v_lshlrev_b32_e32 v118, 16, v101
	v_and_b32_e32 v119, 0xffff0000, v101
	v_lshlrev_b32_e32 v120, 16, v102
	v_and_b32_e32 v121, 0xffff0000, v102
	v_lshlrev_b32_e32 v122, 16, v103
	v_and_b32_e32 v123, 0xffff0000, v103
	v_lshlrev_b32_e32 v124, 16, v104
	v_and_b32_e32 v125, 0xffff0000, v104
	v_lshlrev_b32_e32 v126, 16, v105
	v_and_b32_e32 v127, 0xffff0000, v105
	v_lshlrev_b32_e32 v128, 16, v106
	v_and_b32_e32 v129, 0xffff0000, v106
	v_lshlrev_b32_e32 v130, 16, v107
	v_and_b32_e32 v131, 0xffff0000, v107
	v_lshlrev_b32_e32 v108, 16, v96
	v_and_b32_e32 v109, 0xffff0000, v96
	v_lshlrev_b32_e32 v110, 16, v97
	v_and_b32_e32 v111, 0xffff0000, v97
	v_lshlrev_b32_e32 v112, 16, v98
	v_and_b32_e32 v113, 0xffff0000, v98
	v_lshlrev_b32_e32 v114, 16, v99
	v_and_b32_e32 v115, 0xffff0000, v99
	v_lshlrev_b32_e32 v132, 16, v92
	v_and_b32_e32 v133, 0xffff0000, v92
	v_lshlrev_b32_e32 v134, 16, v93
	v_and_b32_e32 v135, 0xffff0000, v93
	v_lshlrev_b32_e32 v136, 16, v94
	v_and_b32_e32 v137, 0xffff0000, v94
	v_lshlrev_b32_e32 v138, 16, v95
	v_and_b32_e32 v139, 0xffff0000, v95
	v_pk_mul_f32 v[116:117], v[116:117], v[76:77]
	v_pk_mul_f32 v[118:119], v[118:119], v[78:79]
	v_pk_mul_f32 v[120:121], v[120:121], v[80:81]
	v_pk_mul_f32 v[122:123], v[122:123], v[82:83]
	v_pk_fma_f32 v[116:117], v[124:125], v[68:69], v[116:117]
	v_pk_fma_f32 v[118:119], v[126:127], v[70:71], v[118:119]
	v_pk_fma_f32 v[120:121], v[128:129], v[72:73], v[120:121]
	v_pk_fma_f32 v[122:123], v[130:131], v[74:75], v[122:123]
	v_pk_fma_f32 v[108:109], v[84:85], v[108:109], v[116:117]
	v_pk_fma_f32 v[110:111], v[86:87], v[110:111], v[118:119]
	v_pk_fma_f32 v[112:113], v[88:89], v[112:113], v[120:121]
	v_pk_fma_f32 v[114:115], v[90:91], v[114:115], v[122:123]
	v_pk_mul_f32 v[108:109], v[108:109], v[132:133]
	v_pk_mul_f32 v[110:111], v[110:111], v[134:135]
	v_pk_mul_f32 v[112:113], v[112:113], v[136:137]
	v_pk_mul_f32 v[114:115], v[114:115], v[138:139]
	v_cvt_pk_bf16_f32 v140, v108, v109
	v_cvt_pk_bf16_f32 v141, v110, v111
	v_cvt_pk_bf16_f32 v142, v112, v113
	v_cvt_pk_bf16_f32 v143, v114, v115
	global_store_dwordx4 v64, v[140:143], s[40:41]
	s_cmp_gt_i32 s24, 0x103fff
	s_cbranch_scc0 .LBB0_440
	s_branch .LBB0_452

.LBB0_781:
	s_lshl_b32 s1, s0, 8
	v_or_b32_e32 v152, s1, v160
	s_cmp_gt_i32 s2, -1
	v_ashrrev_i32_e32 v153, 31, v152
	s_cbranch_scc1 .LBB0_811
	s_lshl_b32 s24, s10, 8
	v_add_u32_e32 v154, s24, v138
	v_lshlrev_b32_e32 v180, 12, v154
	v_mov_b32_e32 v181, 0
	v_lshl_add_u64 v[180:181], s[6:7], 0, v[180:181]
	v_lshl_add_u64 v[180:181], v[152:153], 1, v[180:181]
	global_load_dwordx4 v[186:189], v[180:181], off
	global_load_dwordx4 v[190:193], v[180:181], off offset:256
	v_add_co_u32_e32 v180, vcc, 0x10000, v180
	s_nop 1
	v_addc_co_u32_e32 v181, vcc, 0, v181, vcc
	global_load_dwordx4 v[194:197], v[180:181], off
	global_load_dwordx4 v[198:201], v[180:181], off offset:256
	v_add_co_u32_e32 v180, vcc, 0x10000, v180
	s_nop 1
	v_addc_co_u32_e32 v181, vcc, 0, v181, vcc
	global_load_dwordx4 v[202:205], v[180:181], off
	global_load_dwordx4 v[206:209], v[180:181], off offset:256
	v_add_co_u32_e32 v180, vcc, 0x10000, v180
	s_nop 1
	v_addc_co_u32_e32 v181, vcc, 0, v181, vcc
	global_load_dwordx4 v[210:213], v[180:181], off
	global_load_dwordx4 v[214:217], v[180:181], off offset:256
	s_waitcnt vmcnt(0)
	v_cmp_gt_i32_e32 vcc, s62, v154
	s_and_saveexec_b64 s[92:93], vcc
	s_cbranch_execz .LBB0_785
	v_ashrrev_i32_e32 v155, 31, v154
	v_lshlrev_b64 v[156:157], 12, v[154:155]
	v_lshl_add_u64 v[156:157], s[6:7], 0, v[156:157]
	v_lshl_add_u64 v[156:157], v[152:153], 1, v[156:157]
	v_mov_b64_e32 v[166:167], v[186:187]
	v_mov_b64_e32 v[168:169], v[188:189]
	v_lshlrev_b32_e32 v170, 16, v166
	v_and_b32_e32 v171, 0xffff0000, v166
	v_lshlrev_b32_e32 v166, 16, v167
	v_and_b32_e32 v167, 0xffff0000, v167
	v_pk_add_f32 v[174:175], v[62:63], v[166:167]
	v_pk_add_f32 v[170:171], v[60:61], v[170:171]
	v_lshlrev_b32_e32 v172, 16, v168
	v_and_b32_e32 v173, 0xffff0000, v168
	v_lshlrev_b32_e32 v168, 16, v169
	v_and_b32_e32 v169, 0xffff0000, v169
	v_mul_f32_e32 v136, v171, v171
	v_mul_f32_e32 v165, v175, v175
	v_pk_add_f32 v[176:177], v[58:59], v[168:169]
	v_pk_add_f32 v[172:173], v[56:57], v[172:173]
	s_nop 1
	v_cvt_pk_bf16_f32 v166, v170, v171
	v_fmac_f32_e32 v136, v170, v170
	v_fmac_f32_e32 v165, v174, v174
	s_nop 1
	v_cvt_pk_bf16_f32 v167, v174, v175
	s_nop 1
	v_cvt_pk_bf16_f32 v168, v172, v173
	s_nop 1
	v_cvt_pk_bf16_f32 v169, v176, v177
	global_store_dwordx4 v[156:157], v[166:169], off
	v_add_f32_e32 v136, v136, v165
	v_mul_f32_e32 v165, v173, v173
	v_mul_f32_e32 v166, v177, v177
	v_fmac_f32_e32 v165, v172, v172
	v_fmac_f32_e32 v166, v176, v176
	v_add_f32_e32 v165, v165, v166
	v_mov_b64_e32 v[166:167], v[190:191]
	v_mov_b64_e32 v[168:169], v[192:193]
	v_add_f32_e32 v136, v136, v165
	v_lshlrev_b32_e32 v170, 16, v166
	v_and_b32_e32 v171, 0xffff0000, v166
	v_lshlrev_b32_e32 v166, 16, v167
	v_and_b32_e32 v167, 0xffff0000, v167
	v_lshlrev_b32_e32 v172, 16, v168
	v_and_b32_e32 v173, 0xffff0000, v168
	v_lshlrev_b32_e32 v168, 16, v169
	v_and_b32_e32 v169, 0xffff0000, v169
	v_pk_add_f32 v[174:175], v[38:39], v[166:167]
	v_pk_add_f32 v[170:171], v[36:37], v[170:171]
	v_pk_add_f32 v[176:177], v[34:35], v[168:169]
	v_pk_add_f32 v[172:173], v[32:33], v[172:173]
	s_nop 1
	v_cvt_pk_bf16_f32 v166, v170, v171
	s_nop 1
	v_cvt_pk_bf16_f32 v167, v174, v175
	v_mul_f32_e32 v165, v177, v177
	s_nop 1
	v_cvt_pk_bf16_f32 v168, v172, v173
	s_nop 1
	v_cvt_pk_bf16_f32 v169, v176, v177
	global_store_dwordx4 v[156:157], v[166:169], off offset:256
	v_mul_f32_e32 v156, v171, v171
	v_mul_f32_e32 v157, v175, v175
	v_fmac_f32_e32 v156, v170, v170
	v_fmac_f32_e32 v157, v174, v174
	v_add_f32_e32 v156, v156, v157
	v_mul_f32_e32 v157, v173, v173
	v_fmac_f32_e32 v157, v172, v172
	v_fmac_f32_e32 v165, v176, v176
	v_add_f32_e32 v157, v157, v165
	v_add_f32_e32 v156, v156, v157
	v_and_b32_e32 v157, 64, v164
	v_add_f32_e32 v136, v136, v156
	v_xor_b32_e32 v156, 16, v164
	v_add_u32_e32 v157, 64, v157
	v_cmp_lt_i32_e32 vcc, v156, v157
	s_nop 1
	v_cndmask_b32_e32 v156, v164, v156, vcc
	v_lshlrev_b32_e32 v156, 2, v156
	ds_bpermute_b32 v156, v156, v136
	s_waitcnt lgkmcnt(0)
	v_add_f32_e32 v136, v136, v156
	v_xor_b32_e32 v156, 32, v164
	v_cmp_lt_i32_e32 vcc, v156, v157
	s_nop 1
	v_cndmask_b32_e32 v156, v164, v156, vcc
	v_lshlrev_b32_e32 v156, 2, v156
	ds_bpermute_b32 v156, v156, v136
	s_and_b64 exec, exec, s[8:9]
	s_cbranch_execz .LBB0_785
	s_waitcnt lgkmcnt(0)
	v_add_f32_e32 v136, v136, v156
	v_lshlrev_b64 v[156:157], 7, v[154:155]
	s_lshl_b32 s14, s0, 2
	v_lshl_add_u64 v[156:157], s[16:17], 0, v[156:157]
	s_ashr_i32 s15, s14, 31
	v_lshl_add_u64 v[156:157], s[14:15], 2, v[156:157]
	s_lshl_b32 s14, s57, 2
	s_mov_b32 s15, s3
	v_lshl_add_u64 v[156:157], v[156:157], 0, s[14:15]
	flat_store_dword v[156:157], v136 sc1
.LBB0_785:
	s_or_b64 exec, exec, s[92:93]
	s_waitcnt lgkmcnt(0)
	v_or_b32_e32 v156, 16, v154
	v_cmp_gt_i32_e32 vcc, s62, v156
	s_and_saveexec_b64 s[92:93], vcc
	s_cbranch_execz .LBB0_788
	v_ashrrev_i32_e32 v157, 31, v156
	v_lshlrev_b64 v[166:167], 12, v[156:157]
	v_lshl_add_u64 v[166:167], s[6:7], 0, v[166:167]
	v_lshl_add_u64 v[170:171], v[152:153], 1, v[166:167]
	v_mov_b64_e32 v[166:167], v[194:195]
	v_mov_b64_e32 v[168:169], v[196:197]
	v_lshlrev_b32_e32 v172, 16, v168
	v_and_b32_e32 v173, 0xffff0000, v168
	v_lshlrev_b32_e32 v168, 16, v169
	v_and_b32_e32 v169, 0xffff0000, v169
	v_pk_add_f32 v[174:175], v[50:51], v[168:169]
	v_lshlrev_b32_e32 v168, 16, v166
	v_and_b32_e32 v169, 0xffff0000, v166
	v_lshlrev_b32_e32 v166, 16, v167
	v_and_b32_e32 v167, 0xffff0000, v167
	v_pk_add_f32 v[172:173], v[48:49], v[172:173]
	v_pk_add_f32 v[176:177], v[54:55], v[166:167]
	v_pk_add_f32 v[178:179], v[52:53], v[168:169]
	v_mul_f32_e32 v155, v177, v177
	s_nop 1
	v_cvt_pk_bf16_f32 v166, v178, v179
	s_nop 1
	v_cvt_pk_bf16_f32 v167, v176, v177
	s_nop 1
	v_cvt_pk_bf16_f32 v168, v172, v173
	s_nop 1
	v_cvt_pk_bf16_f32 v169, v174, v175
	global_store_dwordx4 v[170:171], v[166:169], off
	s_nop 1
	v_mov_b64_e32 v[166:167], v[198:199]
	v_mov_b64_e32 v[168:169], v[200:201]
	v_mul_f32_e32 v136, v179, v179
	v_fmac_f32_e32 v136, v178, v178
	v_fmac_f32_e32 v155, v176, v176
	v_add_f32_e32 v136, v136, v155
	v_mul_f32_e32 v155, v173, v173
	v_mul_f32_e32 v165, v175, v175
	v_fmac_f32_e32 v155, v172, v172
	v_fmac_f32_e32 v165, v174, v174
	v_add_f32_e32 v155, v155, v165
	v_add_f32_e32 v136, v136, v155
	v_lshlrev_b32_e32 v172, 16, v166
	v_and_b32_e32 v173, 0xffff0000, v166
	v_lshlrev_b32_e32 v166, 16, v167
	v_and_b32_e32 v167, 0xffff0000, v167
	v_pk_add_f32 v[176:177], v[22:23], v[166:167]
	v_pk_add_f32 v[172:173], v[20:21], v[172:173]
	v_lshlrev_b32_e32 v174, 16, v168
	v_and_b32_e32 v175, 0xffff0000, v168
	v_lshlrev_b32_e32 v168, 16, v169
	v_and_b32_e32 v169, 0xffff0000, v169
	v_mul_f32_e32 v155, v173, v173
	v_mul_f32_e32 v165, v177, v177
	v_pk_add_f32 v[178:179], v[18:19], v[168:169]
	v_pk_add_f32 v[174:175], v[16:17], v[174:175]
	s_nop 1
	v_cvt_pk_bf16_f32 v166, v172, v173
	v_fmac_f32_e32 v155, v172, v172
	v_fmac_f32_e32 v165, v176, v176
	s_nop 1
	v_cvt_pk_bf16_f32 v167, v176, v177
	s_nop 1
	v_cvt_pk_bf16_f32 v168, v174, v175
	s_nop 1
	v_cvt_pk_bf16_f32 v169, v178, v179
	global_store_dwordx4 v[170:171], v[166:169], off offset:256
	v_add_f32_e32 v155, v155, v165
	v_mul_f32_e32 v165, v175, v175
	v_mul_f32_e32 v166, v179, v179
	v_fmac_f32_e32 v165, v174, v174
	v_fmac_f32_e32 v166, v178, v178
	v_add_f32_e32 v165, v165, v166
	v_add_f32_e32 v155, v155, v165
	v_and_b32_e32 v165, 64, v164
	v_add_f32_e32 v136, v136, v155
	v_xor_b32_e32 v155, 16, v164
	v_add_u32_e32 v165, 64, v165
	v_cmp_lt_i32_e32 vcc, v155, v165
	s_nop 1
	v_cndmask_b32_e32 v155, v164, v155, vcc
	v_lshlrev_b32_e32 v155, 2, v155
	ds_bpermute_b32 v155, v155, v136
	s_waitcnt lgkmcnt(0)
	v_add_f32_e32 v136, v136, v155
	v_xor_b32_e32 v155, 32, v164
	v_cmp_lt_i32_e32 vcc, v155, v165
	s_nop 1
	v_cndmask_b32_e32 v155, v164, v155, vcc
	v_lshlrev_b32_e32 v155, 2, v155
	ds_bpermute_b32 v155, v155, v136
	s_and_b64 exec, exec, s[8:9]
	s_cbranch_execz .LBB0_788
	v_lshlrev_b64 v[156:157], 7, v[156:157]
	s_lshl_b32 s14, s0, 2
	v_lshl_add_u64 v[156:157], s[16:17], 0, v[156:157]
	s_ashr_i32 s15, s14, 31
	v_lshl_add_u64 v[156:157], s[14:15], 2, v[156:157]
	s_lshl_b32 s14, s57, 2
	s_mov_b32 s15, s3
	s_waitcnt lgkmcnt(0)
	v_add_f32_e32 v136, v136, v155
	v_lshl_add_u64 v[156:157], v[156:157], 0, s[14:15]
	flat_store_dword v[156:157], v136 sc1
.LBB0_788:
	s_or_b64 exec, exec, s[92:93]
	v_or_b32_e32 v156, 32, v154
	v_cmp_gt_i32_e32 vcc, s62, v156
	s_and_saveexec_b64 s[92:93], vcc
	s_cbranch_execz .LBB0_791
	v_ashrrev_i32_e32 v157, 31, v156
	v_lshlrev_b64 v[166:167], 12, v[156:157]
	v_lshl_add_u64 v[166:167], s[6:7], 0, v[166:167]
	v_lshl_add_u64 v[170:171], v[152:153], 1, v[166:167]
	v_mov_b64_e32 v[166:167], v[202:203]
	v_mov_b64_e32 v[168:169], v[204:205]
	v_lshlrev_b32_e32 v172, 16, v168
	v_and_b32_e32 v173, 0xffff0000, v168
	v_lshlrev_b32_e32 v168, 16, v169
	v_and_b32_e32 v169, 0xffff0000, v169
	v_pk_add_f32 v[174:175], v[42:43], v[168:169]
	v_lshlrev_b32_e32 v168, 16, v166
	v_and_b32_e32 v169, 0xffff0000, v166
	v_lshlrev_b32_e32 v166, 16, v167
	v_and_b32_e32 v167, 0xffff0000, v167
	v_pk_add_f32 v[172:173], v[40:41], v[172:173]
	v_pk_add_f32 v[176:177], v[46:47], v[166:167]
	v_pk_add_f32 v[178:179], v[44:45], v[168:169]
	s_waitcnt lgkmcnt(0)
	v_mul_f32_e32 v155, v177, v177
	s_nop 1
	v_cvt_pk_bf16_f32 v166, v178, v179
	s_nop 1
	v_cvt_pk_bf16_f32 v167, v176, v177
	s_nop 1
	v_cvt_pk_bf16_f32 v168, v172, v173
	s_nop 1
	v_cvt_pk_bf16_f32 v169, v174, v175
	global_store_dwordx4 v[170:171], v[166:169], off
	s_nop 1
	v_mov_b64_e32 v[166:167], v[206:207]
	v_mov_b64_e32 v[168:169], v[208:209]
	v_mul_f32_e32 v136, v179, v179
	v_fmac_f32_e32 v136, v178, v178
	v_fmac_f32_e32 v155, v176, v176
	v_add_f32_e32 v136, v136, v155
	v_mul_f32_e32 v155, v173, v173
	v_mul_f32_e32 v165, v175, v175
	v_fmac_f32_e32 v155, v172, v172
	v_fmac_f32_e32 v165, v174, v174
	v_add_f32_e32 v155, v155, v165
	v_add_f32_e32 v136, v136, v155
	v_lshlrev_b32_e32 v172, 16, v166
	v_and_b32_e32 v173, 0xffff0000, v166
	v_lshlrev_b32_e32 v166, 16, v167
	v_and_b32_e32 v167, 0xffff0000, v167
	v_pk_add_f32 v[176:177], v[14:15], v[166:167]
	v_pk_add_f32 v[172:173], v[12:13], v[172:173]
	v_lshlrev_b32_e32 v174, 16, v168
	v_and_b32_e32 v175, 0xffff0000, v168
	v_lshlrev_b32_e32 v168, 16, v169
	v_and_b32_e32 v169, 0xffff0000, v169
	v_mul_f32_e32 v155, v173, v173
	v_mul_f32_e32 v165, v177, v177
	v_pk_add_f32 v[178:179], v[10:11], v[168:169]
	v_pk_add_f32 v[174:175], v[8:9], v[174:175]
	s_nop 1
	v_cvt_pk_bf16_f32 v166, v172, v173
	v_fmac_f32_e32 v155, v172, v172
	v_fmac_f32_e32 v165, v176, v176
	s_nop 1
	v_cvt_pk_bf16_f32 v167, v176, v177
	s_nop 1
	v_cvt_pk_bf16_f32 v168, v174, v175
	s_nop 1
	v_cvt_pk_bf16_f32 v169, v178, v179
	global_store_dwordx4 v[170:171], v[166:169], off offset:256
	v_add_f32_e32 v155, v155, v165
	v_mul_f32_e32 v165, v175, v175
	v_mul_f32_e32 v166, v179, v179
	v_fmac_f32_e32 v165, v174, v174
	v_fmac_f32_e32 v166, v178, v178
	v_add_f32_e32 v165, v165, v166
	v_add_f32_e32 v155, v155, v165
	v_and_b32_e32 v165, 64, v164
	v_add_f32_e32 v136, v136, v155
	v_xor_b32_e32 v155, 16, v164
	v_add_u32_e32 v165, 64, v165
	v_cmp_lt_i32_e32 vcc, v155, v165
	s_nop 1
	v_cndmask_b32_e32 v155, v164, v155, vcc
	v_lshlrev_b32_e32 v155, 2, v155
	ds_bpermute_b32 v155, v155, v136
	s_waitcnt lgkmcnt(0)
	v_add_f32_e32 v136, v136, v155
	v_xor_b32_e32 v155, 32, v164
	v_cmp_lt_i32_e32 vcc, v155, v165
	s_nop 1
	v_cndmask_b32_e32 v155, v164, v155, vcc
	v_lshlrev_b32_e32 v155, 2, v155
	ds_bpermute_b32 v155, v155, v136
	s_and_b64 exec, exec, s[8:9]
	s_cbranch_execz .LBB0_791
	v_lshlrev_b64 v[156:157], 7, v[156:157]
	s_lshl_b32 s14, s0, 2
	v_lshl_add_u64 v[156:157], s[16:17], 0, v[156:157]
	s_ashr_i32 s15, s14, 31
	v_lshl_add_u64 v[156:157], s[14:15], 2, v[156:157]
	s_lshl_b32 s14, s57, 2
	s_mov_b32 s15, s3
	s_waitcnt lgkmcnt(0)
	v_add_f32_e32 v136, v136, v155
	v_lshl_add_u64 v[156:157], v[156:157], 0, s[14:15]
	flat_store_dword v[156:157], v136 sc1
.LBB0_791:
	s_or_b64 exec, exec, s[92:93]
	v_or_b32_e32 v156, 48, v154
	v_cmp_gt_i32_e32 vcc, s62, v156
	s_and_saveexec_b64 s[92:93], vcc
	s_cbranch_execz .LBB0_794
	v_ashrrev_i32_e32 v157, 31, v156
	v_lshlrev_b64 v[166:167], 12, v[156:157]
	v_lshl_add_u64 v[166:167], s[6:7], 0, v[166:167]
	v_lshl_add_u64 v[170:171], v[152:153], 1, v[166:167]
	v_mov_b64_e32 v[166:167], v[210:211]
	v_mov_b64_e32 v[168:169], v[212:213]
	v_lshlrev_b32_e32 v172, 16, v168
	v_and_b32_e32 v173, 0xffff0000, v168
	v_lshlrev_b32_e32 v168, 16, v169
	v_and_b32_e32 v169, 0xffff0000, v169
	v_pk_add_f32 v[174:175], v[26:27], v[168:169]
	v_lshlrev_b32_e32 v168, 16, v166
	v_and_b32_e32 v169, 0xffff0000, v166
	v_lshlrev_b32_e32 v166, 16, v167
	v_and_b32_e32 v167, 0xffff0000, v167
	v_pk_add_f32 v[172:173], v[24:25], v[172:173]
	v_pk_add_f32 v[176:177], v[30:31], v[166:167]
	v_pk_add_f32 v[178:179], v[28:29], v[168:169]
	s_waitcnt lgkmcnt(0)
	v_mul_f32_e32 v155, v177, v177
	s_nop 1
	v_cvt_pk_bf16_f32 v166, v178, v179
	s_nop 1
	v_cvt_pk_bf16_f32 v167, v176, v177
	s_nop 1
	v_cvt_pk_bf16_f32 v168, v172, v173
	s_nop 1
	v_cvt_pk_bf16_f32 v169, v174, v175
	global_store_dwordx4 v[170:171], v[166:169], off
	s_nop 1
	v_mov_b64_e32 v[166:167], v[214:215]
	v_mov_b64_e32 v[168:169], v[216:217]
	v_mul_f32_e32 v136, v179, v179
	v_fmac_f32_e32 v136, v178, v178
	v_fmac_f32_e32 v155, v176, v176
	v_add_f32_e32 v136, v136, v155
	v_mul_f32_e32 v155, v173, v173
	v_mul_f32_e32 v165, v175, v175
	v_fmac_f32_e32 v155, v172, v172
	v_fmac_f32_e32 v165, v174, v174
	v_add_f32_e32 v155, v155, v165
	v_add_f32_e32 v136, v136, v155
	v_lshlrev_b32_e32 v172, 16, v166
	v_and_b32_e32 v173, 0xffff0000, v166
	v_lshlrev_b32_e32 v166, 16, v167
	v_and_b32_e32 v167, 0xffff0000, v167
	v_pk_add_f32 v[176:177], v[6:7], v[166:167]
	v_pk_add_f32 v[172:173], v[4:5], v[172:173]
	v_lshlrev_b32_e32 v174, 16, v168
	v_and_b32_e32 v175, 0xffff0000, v168
	v_lshlrev_b32_e32 v168, 16, v169
	v_and_b32_e32 v169, 0xffff0000, v169
	v_mul_f32_e32 v155, v173, v173
	v_mul_f32_e32 v165, v177, v177
	v_pk_add_f32 v[178:179], v[2:3], v[168:169]
	v_pk_add_f32 v[174:175], v[0:1], v[174:175]
	s_nop 1
	v_cvt_pk_bf16_f32 v166, v172, v173
	v_fmac_f32_e32 v155, v172, v172
	v_fmac_f32_e32 v165, v176, v176
	s_nop 1
	v_cvt_pk_bf16_f32 v167, v176, v177
	s_nop 1
	v_cvt_pk_bf16_f32 v168, v174, v175
	s_nop 1
	v_cvt_pk_bf16_f32 v169, v178, v179
	global_store_dwordx4 v[170:171], v[166:169], off offset:256
	v_add_f32_e32 v155, v155, v165
	v_mul_f32_e32 v165, v175, v175
	v_mul_f32_e32 v166, v179, v179
	v_fmac_f32_e32 v165, v174, v174
	v_fmac_f32_e32 v166, v178, v178
	v_add_f32_e32 v165, v165, v166
	v_add_f32_e32 v155, v155, v165
	v_and_b32_e32 v165, 64, v164
	v_add_f32_e32 v136, v136, v155
	v_xor_b32_e32 v155, 16, v164
	v_add_u32_e32 v165, 64, v165
	v_cmp_lt_i32_e32 vcc, v155, v165
	s_nop 1
	v_cndmask_b32_e32 v155, v164, v155, vcc
	v_lshlrev_b32_e32 v155, 2, v155
	ds_bpermute_b32 v155, v155, v136
	s_waitcnt lgkmcnt(0)
	v_add_f32_e32 v136, v136, v155
	v_xor_b32_e32 v155, 32, v164
	v_cmp_lt_i32_e32 vcc, v155, v165
	s_nop 1
	v_cndmask_b32_e32 v155, v164, v155, vcc
	v_lshlrev_b32_e32 v155, 2, v155
	ds_bpermute_b32 v155, v155, v136
	s_and_b64 exec, exec, s[8:9]
	s_cbranch_execz .LBB0_794
	v_lshlrev_b64 v[156:157], 7, v[156:157]
	s_lshl_b32 s14, s0, 2
	v_lshl_add_u64 v[156:157], s[16:17], 0, v[156:157]
	s_ashr_i32 s15, s14, 31
	v_lshl_add_u64 v[156:157], s[14:15], 2, v[156:157]
	s_lshl_b32 s14, s57, 2
	s_mov_b32 s15, s3
	s_waitcnt lgkmcnt(0)
	v_add_f32_e32 v136, v136, v155
	v_lshl_add_u64 v[156:157], v[156:157], 0, s[14:15]
	flat_store_dword v[156:157], v136 sc1
.LBB0_794:
	s_or_b64 exec, exec, s[92:93]
	s_movk_i32 s11, 0x2080
	v_lshlrev_b32_e32 v180, 12, v154
	v_mov_b32_e32 v181, 0
	v_lshl_add_u64 v[180:181], s[6:7], 0, v[180:181]
	v_lshl_add_u64 v[180:181], v[152:153], 1, v[180:181]
	v_add_co_u32_e32 v180, vcc, 0x80000, v180
	s_nop 1
	v_addc_co_u32_e32 v181, vcc, 0, v181, vcc
	global_load_dwordx4 v[186:189], v[180:181], off
	global_load_dwordx4 v[190:193], v[180:181], off offset:256
	v_add_co_u32_e32 v180, vcc, 0x10000, v180
	s_nop 1
	v_addc_co_u32_e32 v181, vcc, 0, v181, vcc
	global_load_dwordx4 v[194:197], v[180:181], off
	global_load_dwordx4 v[198:201], v[180:181], off offset:256
	v_add_co_u32_e32 v180, vcc, 0x10000, v180
	s_nop 1
	v_addc_co_u32_e32 v181, vcc, 0, v181, vcc
	global_load_dwordx4 v[202:205], v[180:181], off
	global_load_dwordx4 v[206:209], v[180:181], off offset:256
	v_add_co_u32_e32 v180, vcc, 0x10000, v180
	s_nop 1
	v_addc_co_u32_e32 v181, vcc, 0, v181, vcc
	global_load_dwordx4 v[210:213], v[180:181], off
	global_load_dwordx4 v[214:217], v[180:181], off offset:256
	s_waitcnt vmcnt(0)
	v_cmp_gt_i32_e32 vcc, s11, v154
	s_and_saveexec_b64 s[92:93], vcc
	s_cbranch_execz .LBB0_797
	v_add_u32_e32 v156, 0x80, v154
	v_ashrrev_i32_e32 v157, 31, v156
	v_lshlrev_b64 v[166:167], 12, v[156:157]
	v_lshl_add_u64 v[166:167], s[6:7], 0, v[166:167]
	v_lshl_add_u64 v[170:171], v[152:153], 1, v[166:167]
	v_mov_b64_e32 v[166:167], v[186:187]
	v_mov_b64_e32 v[168:169], v[188:189]
	v_lshlrev_b32_e32 v172, 16, v168
	v_and_b32_e32 v173, 0xffff0000, v168
	v_lshlrev_b32_e32 v168, 16, v169
	v_and_b32_e32 v169, 0xffff0000, v169
	v_pk_add_f32 v[126:127], v[126:127], v[168:169]
	v_lshlrev_b32_e32 v168, 16, v166
	v_and_b32_e32 v169, 0xffff0000, v166
	v_lshlrev_b32_e32 v166, 16, v167
	v_and_b32_e32 v167, 0xffff0000, v167
	v_pk_add_f32 v[166:167], v[122:123], v[166:167]
	v_pk_add_f32 v[168:169], v[120:121], v[168:169]
	v_pk_add_f32 v[124:125], v[124:125], v[172:173]
	s_nop 1
	v_cvt_pk_bf16_f32 v120, v168, v169
	s_nop 1
	v_cvt_pk_bf16_f32 v121, v166, v167
	s_nop 0
	s_nop 1
	v_cvt_pk_bf16_f32 v122, v124, v125
	s_nop 1
	v_cvt_pk_bf16_f32 v123, v126, v127
	global_store_dwordx4 v[170:171], v[120:123], off
	s_nop 1
	v_mul_f32_e32 v120, v169, v169
	v_mul_f32_e32 v121, v167, v167
	v_fmac_f32_e32 v120, v168, v168
	v_fmac_f32_e32 v121, v166, v166
	v_add_f32_e32 v120, v120, v121
	v_mul_f32_e32 v121, v125, v125
	v_mul_f32_e32 v122, v127, v127
	v_fmac_f32_e32 v121, v124, v124
	v_fmac_f32_e32 v122, v126, v126
	v_add_f32_e32 v121, v121, v122
	v_add_f32_e32 v136, v120, v121
	v_mov_b64_e32 v[120:121], v[190:191]
	v_mov_b64_e32 v[122:123], v[192:193]
	v_lshlrev_b32_e32 v124, 16, v120
	v_and_b32_e32 v125, 0xffff0000, v120
	v_lshlrev_b32_e32 v120, 16, v121
	v_and_b32_e32 v121, 0xffff0000, v121
	v_lshlrev_b32_e32 v126, 16, v122
	v_and_b32_e32 v127, 0xffff0000, v122
	v_lshlrev_b32_e32 v122, 16, v123
	v_and_b32_e32 v123, 0xffff0000, v123
	v_pk_add_f32 v[118:119], v[118:119], v[120:121]
	v_pk_add_f32 v[116:117], v[116:117], v[124:125]
	v_pk_add_f32 v[120:121], v[114:115], v[122:123]
	v_pk_add_f32 v[122:123], v[112:113], v[126:127]
	s_nop 1
	v_cvt_pk_bf16_f32 v112, v116, v117
	s_nop 1
	v_cvt_pk_bf16_f32 v113, v118, v119
	s_nop 0
	s_nop 1
	v_cvt_pk_bf16_f32 v114, v122, v123
	s_nop 1
	v_cvt_pk_bf16_f32 v115, v120, v121
	global_store_dwordx4 v[170:171], v[112:115], off offset:256
	s_nop 1
	v_mul_f32_e32 v112, v117, v117
	v_mul_f32_e32 v113, v119, v119
	v_fmac_f32_e32 v112, v116, v116
	v_fmac_f32_e32 v113, v118, v118
	v_add_f32_e32 v112, v112, v113
	v_mul_f32_e32 v113, v123, v123
	v_mul_f32_e32 v114, v121, v121
	v_fmac_f32_e32 v113, v122, v122
	v_fmac_f32_e32 v114, v120, v120
	v_add_f32_e32 v113, v113, v114
	v_and_b32_e32 v114, 64, v164
	v_add_f32_e32 v112, v112, v113
	v_xor_b32_e32 v113, 16, v164
	v_add_u32_e32 v114, 64, v114
	v_cmp_lt_i32_e32 vcc, v113, v114
	v_add_f32_e32 v112, v136, v112
	s_nop 0
	v_cndmask_b32_e32 v113, v164, v113, vcc
	v_lshlrev_b32_e32 v113, 2, v113
	ds_bpermute_b32 v113, v113, v112
	s_waitcnt lgkmcnt(0)
	v_add_f32_e32 v112, v112, v113
	v_xor_b32_e32 v113, 32, v164
	v_cmp_lt_i32_e32 vcc, v113, v114
	s_nop 1
	v_cndmask_b32_e32 v113, v164, v113, vcc
	v_lshlrev_b32_e32 v113, 2, v113
	ds_bpermute_b32 v113, v113, v112
	s_and_b64 exec, exec, s[8:9]
	s_cbranch_execz .LBB0_797
	s_waitcnt lgkmcnt(0)
	v_add_f32_e32 v114, v112, v113
	v_lshlrev_b64 v[112:113], 7, v[156:157]
	s_lshl_b32 s14, s0, 2
	v_lshl_add_u64 v[112:113], s[16:17], 0, v[112:113]
	s_ashr_i32 s15, s14, 31
	v_lshl_add_u64 v[112:113], s[14:15], 2, v[112:113]
	s_lshl_b32 s14, s57, 2
	s_mov_b32 s15, s3
	v_lshl_add_u64 v[112:113], v[112:113], 0, s[14:15]
	flat_store_dword v[112:113], v114 sc1
.LBB0_797:
	s_or_b64 exec, exec, s[92:93]
	s_movk_i32 s11, 0x2070
	v_cmp_gt_i32_e32 vcc, s11, v154
	s_and_saveexec_b64 s[92:93], vcc
	s_cbranch_execz .LBB0_800
	v_add_u32_e32 v112, 0x90, v154
	s_waitcnt lgkmcnt(0)
	v_ashrrev_i32_e32 v113, 31, v112
	v_lshlrev_b64 v[114:115], 12, v[112:113]
	v_lshl_add_u64 v[114:115], s[6:7], 0, v[114:115]
	v_lshl_add_u64 v[118:119], v[152:153], 1, v[114:115]
	v_mov_b64_e32 v[114:115], v[194:195]
	v_mov_b64_e32 v[116:117], v[196:197]
	v_lshlrev_b32_e32 v120, 16, v116
	v_and_b32_e32 v121, 0xffff0000, v116
	v_lshlrev_b32_e32 v116, 16, v117
	v_and_b32_e32 v117, 0xffff0000, v117
	v_pk_add_f32 v[110:111], v[110:111], v[116:117]
	v_lshlrev_b32_e32 v116, 16, v114
	v_and_b32_e32 v117, 0xffff0000, v114
	v_lshlrev_b32_e32 v114, 16, v115
	v_and_b32_e32 v115, 0xffff0000, v115
	v_pk_add_f32 v[114:115], v[106:107], v[114:115]
	v_pk_add_f32 v[116:117], v[104:105], v[116:117]
	v_pk_add_f32 v[108:109], v[108:109], v[120:121]
	s_nop 1
	v_cvt_pk_bf16_f32 v104, v116, v117
	s_nop 1
	v_cvt_pk_bf16_f32 v105, v114, v115
	s_nop 0
	s_nop 1
	v_cvt_pk_bf16_f32 v106, v108, v109
	s_nop 1
	v_cvt_pk_bf16_f32 v107, v110, v111
	global_store_dwordx4 v[118:119], v[104:107], off
	s_nop 1
	v_mul_f32_e32 v104, v117, v117
	v_mul_f32_e32 v105, v115, v115
	v_fmac_f32_e32 v104, v116, v116
	v_fmac_f32_e32 v105, v114, v114
	v_add_f32_e32 v104, v104, v105
	v_mul_f32_e32 v105, v109, v109
	v_mul_f32_e32 v106, v111, v111
	v_fmac_f32_e32 v105, v108, v108
	v_fmac_f32_e32 v106, v110, v110
	v_add_f32_e32 v105, v105, v106
	v_add_f32_e32 v114, v104, v105
	v_mov_b64_e32 v[104:105], v[198:199]
	v_mov_b64_e32 v[106:107], v[200:201]
	v_lshlrev_b32_e32 v108, 16, v104
	v_and_b32_e32 v109, 0xffff0000, v104
	v_lshlrev_b32_e32 v104, 16, v105
	v_and_b32_e32 v105, 0xffff0000, v105
	v_lshlrev_b32_e32 v110, 16, v106
	v_and_b32_e32 v111, 0xffff0000, v106
	v_lshlrev_b32_e32 v106, 16, v107
	v_and_b32_e32 v107, 0xffff0000, v107
	v_pk_add_f32 v[102:103], v[102:103], v[104:105]
	v_pk_add_f32 v[100:101], v[100:101], v[108:109]
	v_pk_add_f32 v[104:105], v[98:99], v[106:107]
	v_pk_add_f32 v[106:107], v[96:97], v[110:111]
	s_nop 1
	v_cvt_pk_bf16_f32 v96, v100, v101
	s_nop 1
	v_cvt_pk_bf16_f32 v97, v102, v103
	s_nop 0
	s_nop 1
	v_cvt_pk_bf16_f32 v98, v106, v107
	s_nop 1
	v_cvt_pk_bf16_f32 v99, v104, v105
	global_store_dwordx4 v[118:119], v[96:99], off offset:256
	s_nop 1
	v_mul_f32_e32 v96, v101, v101
	v_mul_f32_e32 v97, v103, v103
	v_fmac_f32_e32 v96, v100, v100
	v_fmac_f32_e32 v97, v102, v102
	v_add_f32_e32 v96, v96, v97
	v_mul_f32_e32 v97, v107, v107
	v_mul_f32_e32 v98, v105, v105
	v_fmac_f32_e32 v97, v106, v106
	v_fmac_f32_e32 v98, v104, v104
	v_add_f32_e32 v97, v97, v98
	v_and_b32_e32 v98, 64, v164
	v_add_f32_e32 v96, v96, v97
	v_xor_b32_e32 v97, 16, v164
	v_add_u32_e32 v98, 64, v98
	v_cmp_lt_i32_e32 vcc, v97, v98
	v_add_f32_e32 v96, v114, v96
	s_nop 0
	v_cndmask_b32_e32 v97, v164, v97, vcc
	v_lshlrev_b32_e32 v97, 2, v97
	ds_bpermute_b32 v97, v97, v96
	s_waitcnt lgkmcnt(0)
	v_add_f32_e32 v96, v96, v97
	v_xor_b32_e32 v97, 32, v164
	v_cmp_lt_i32_e32 vcc, v97, v98
	s_nop 1
	v_cndmask_b32_e32 v97, v164, v97, vcc
	v_lshlrev_b32_e32 v97, 2, v97
	ds_bpermute_b32 v97, v97, v96
	s_and_b64 exec, exec, s[8:9]
	s_cbranch_execz .LBB0_800
	s_waitcnt lgkmcnt(0)
	v_add_f32_e32 v98, v96, v97
	v_lshlrev_b64 v[96:97], 7, v[112:113]
	s_lshl_b32 s14, s0, 2
	v_lshl_add_u64 v[96:97], s[16:17], 0, v[96:97]
	s_ashr_i32 s15, s14, 31
	v_lshl_add_u64 v[96:97], s[14:15], 2, v[96:97]
	s_lshl_b32 s14, s57, 2
	s_mov_b32 s15, s3
	v_lshl_add_u64 v[96:97], v[96:97], 0, s[14:15]
	flat_store_dword v[96:97], v98 sc1
.LBB0_800:
	s_or_b64 exec, exec, s[92:93]
	s_movk_i32 s11, 0x2060
	v_cmp_gt_i32_e32 vcc, s11, v154
	s_and_saveexec_b64 s[92:93], vcc
	s_cbranch_execz .LBB0_803
	v_add_u32_e32 v96, 0xa0, v154
	s_waitcnt lgkmcnt(0)
	v_ashrrev_i32_e32 v97, 31, v96
	v_lshlrev_b64 v[98:99], 12, v[96:97]
	v_lshl_add_u64 v[98:99], s[6:7], 0, v[98:99]
	v_lshl_add_u64 v[102:103], v[152:153], 1, v[98:99]
	v_mov_b64_e32 v[98:99], v[202:203]
	v_mov_b64_e32 v[100:101], v[204:205]
	v_lshlrev_b32_e32 v104, 16, v100
	v_and_b32_e32 v105, 0xffff0000, v100
	v_lshlrev_b32_e32 v100, 16, v101
	v_and_b32_e32 v101, 0xffff0000, v101
	v_pk_add_f32 v[94:95], v[94:95], v[100:101]
	v_lshlrev_b32_e32 v100, 16, v98
	v_and_b32_e32 v101, 0xffff0000, v98
	v_lshlrev_b32_e32 v98, 16, v99
	v_and_b32_e32 v99, 0xffff0000, v99
	v_pk_add_f32 v[98:99], v[90:91], v[98:99]
	v_pk_add_f32 v[100:101], v[88:89], v[100:101]
	v_pk_add_f32 v[92:93], v[92:93], v[104:105]
	s_nop 1
	v_cvt_pk_bf16_f32 v88, v100, v101
	s_nop 1
	v_cvt_pk_bf16_f32 v89, v98, v99
	s_nop 0
	s_nop 1
	v_cvt_pk_bf16_f32 v90, v92, v93
	s_nop 1
	v_cvt_pk_bf16_f32 v91, v94, v95
	global_store_dwordx4 v[102:103], v[88:91], off
	s_nop 1
	v_mul_f32_e32 v88, v101, v101
	v_mul_f32_e32 v89, v99, v99
	v_fmac_f32_e32 v88, v100, v100
	v_fmac_f32_e32 v89, v98, v98
	v_add_f32_e32 v88, v88, v89
	v_mul_f32_e32 v89, v93, v93
	v_mul_f32_e32 v90, v95, v95
	v_fmac_f32_e32 v89, v92, v92
	v_fmac_f32_e32 v90, v94, v94
	v_add_f32_e32 v89, v89, v90
	v_add_f32_e32 v98, v88, v89
	v_mov_b64_e32 v[88:89], v[206:207]
	v_mov_b64_e32 v[90:91], v[208:209]
	v_lshlrev_b32_e32 v92, 16, v88
	v_and_b32_e32 v93, 0xffff0000, v88
	v_lshlrev_b32_e32 v88, 16, v89
	v_and_b32_e32 v89, 0xffff0000, v89
	v_lshlrev_b32_e32 v94, 16, v90
	v_and_b32_e32 v95, 0xffff0000, v90
	v_lshlrev_b32_e32 v90, 16, v91
	v_and_b32_e32 v91, 0xffff0000, v91
	v_pk_add_f32 v[86:87], v[86:87], v[88:89]
	v_pk_add_f32 v[84:85], v[84:85], v[92:93]
	v_pk_add_f32 v[88:89], v[82:83], v[90:91]
	v_pk_add_f32 v[90:91], v[80:81], v[94:95]
	s_nop 1
	v_cvt_pk_bf16_f32 v80, v84, v85
	s_nop 1
	v_cvt_pk_bf16_f32 v81, v86, v87
	s_nop 0
	s_nop 1
	v_cvt_pk_bf16_f32 v82, v90, v91
	s_nop 1
	v_cvt_pk_bf16_f32 v83, v88, v89
	global_store_dwordx4 v[102:103], v[80:83], off offset:256
	s_nop 1
	v_mul_f32_e32 v80, v85, v85
	v_mul_f32_e32 v81, v87, v87
	v_fmac_f32_e32 v80, v84, v84
	v_fmac_f32_e32 v81, v86, v86
	v_add_f32_e32 v80, v80, v81
	v_mul_f32_e32 v81, v91, v91
	v_mul_f32_e32 v82, v89, v89
	v_fmac_f32_e32 v81, v90, v90
	v_fmac_f32_e32 v82, v88, v88
	v_add_f32_e32 v81, v81, v82
	v_and_b32_e32 v82, 64, v164
	v_add_f32_e32 v80, v80, v81
	v_xor_b32_e32 v81, 16, v164
	v_add_u32_e32 v82, 64, v82
	v_cmp_lt_i32_e32 vcc, v81, v82
	v_add_f32_e32 v80, v98, v80
	s_nop 0
	v_cndmask_b32_e32 v81, v164, v81, vcc
	v_lshlrev_b32_e32 v81, 2, v81
	ds_bpermute_b32 v81, v81, v80
	s_waitcnt lgkmcnt(0)
	v_add_f32_e32 v80, v80, v81
	v_xor_b32_e32 v81, 32, v164
	v_cmp_lt_i32_e32 vcc, v81, v82
	s_nop 1
	v_cndmask_b32_e32 v81, v164, v81, vcc
	v_lshlrev_b32_e32 v81, 2, v81
	ds_bpermute_b32 v81, v81, v80
	s_and_b64 exec, exec, s[8:9]
	s_cbranch_execz .LBB0_803
	s_waitcnt lgkmcnt(0)
	v_add_f32_e32 v82, v80, v81
	v_lshlrev_b64 v[80:81], 7, v[96:97]
	s_lshl_b32 s14, s0, 2
	v_lshl_add_u64 v[80:81], s[16:17], 0, v[80:81]
	s_ashr_i32 s15, s14, 31
	v_lshl_add_u64 v[80:81], s[14:15], 2, v[80:81]
	s_lshl_b32 s14, s57, 2
	s_mov_b32 s15, s3
	v_lshl_add_u64 v[80:81], v[80:81], 0, s[14:15]
	flat_store_dword v[80:81], v82 sc1
.LBB0_803:
	s_or_b64 exec, exec, s[92:93]
	s_movk_i32 s11, 0x2050
	v_cmp_gt_i32_e32 vcc, s11, v154
	s_and_saveexec_b64 s[92:93], vcc
	s_cbranch_execz .LBB0_806
	v_add_u32_e32 v80, 0xb0, v154
	s_waitcnt lgkmcnt(0)
	v_ashrrev_i32_e32 v81, 31, v80
	v_lshlrev_b64 v[82:83], 12, v[80:81]
	v_lshl_add_u64 v[82:83], s[6:7], 0, v[82:83]
	v_lshl_add_u64 v[86:87], v[152:153], 1, v[82:83]
	v_mov_b64_e32 v[82:83], v[210:211]
	v_mov_b64_e32 v[84:85], v[212:213]
	v_lshlrev_b32_e32 v88, 16, v84
	v_and_b32_e32 v89, 0xffff0000, v84
	v_lshlrev_b32_e32 v84, 16, v85
	v_and_b32_e32 v85, 0xffff0000, v85
	v_pk_add_f32 v[78:79], v[78:79], v[84:85]
	v_lshlrev_b32_e32 v84, 16, v82
	v_and_b32_e32 v85, 0xffff0000, v82
	v_lshlrev_b32_e32 v82, 16, v83
	v_and_b32_e32 v83, 0xffff0000, v83
	v_pk_add_f32 v[82:83], v[74:75], v[82:83]
	v_pk_add_f32 v[84:85], v[72:73], v[84:85]
	v_pk_add_f32 v[76:77], v[76:77], v[88:89]
	s_nop 1
	v_cvt_pk_bf16_f32 v72, v84, v85
	s_nop 1
	v_cvt_pk_bf16_f32 v73, v82, v83
	s_nop 0
	s_nop 1
	v_cvt_pk_bf16_f32 v74, v76, v77
	s_nop 1
	v_cvt_pk_bf16_f32 v75, v78, v79
	global_store_dwordx4 v[86:87], v[72:75], off
	s_nop 1
	v_mul_f32_e32 v72, v85, v85
	v_mul_f32_e32 v73, v83, v83
	v_fmac_f32_e32 v72, v84, v84
	v_fmac_f32_e32 v73, v82, v82
	v_add_f32_e32 v72, v72, v73
	v_mul_f32_e32 v73, v77, v77
	v_mul_f32_e32 v74, v79, v79
	v_fmac_f32_e32 v73, v76, v76
	v_fmac_f32_e32 v74, v78, v78
	v_add_f32_e32 v73, v73, v74
	v_add_f32_e32 v82, v72, v73
	v_mov_b64_e32 v[72:73], v[214:215]
	v_mov_b64_e32 v[74:75], v[216:217]
	v_lshlrev_b32_e32 v76, 16, v72
	v_and_b32_e32 v77, 0xffff0000, v72
	v_lshlrev_b32_e32 v72, 16, v73
	v_and_b32_e32 v73, 0xffff0000, v73
	v_lshlrev_b32_e32 v78, 16, v74
	v_and_b32_e32 v79, 0xffff0000, v74
	v_lshlrev_b32_e32 v74, 16, v75
	v_and_b32_e32 v75, 0xffff0000, v75
	v_pk_add_f32 v[70:71], v[70:71], v[72:73]
	v_pk_add_f32 v[68:69], v[68:69], v[76:77]
	v_pk_add_f32 v[72:73], v[66:67], v[74:75]
	v_pk_add_f32 v[74:75], v[64:65], v[78:79]
	s_nop 1
	v_cvt_pk_bf16_f32 v64, v68, v69
	s_nop 1
	v_cvt_pk_bf16_f32 v65, v70, v71
	s_nop 0
	s_nop 1
	v_cvt_pk_bf16_f32 v66, v74, v75
	s_nop 1
	v_cvt_pk_bf16_f32 v67, v72, v73
	global_store_dwordx4 v[86:87], v[64:67], off offset:256
	s_nop 1
	v_mul_f32_e32 v64, v69, v69
	v_mul_f32_e32 v65, v71, v71
	v_fmac_f32_e32 v64, v68, v68
	v_fmac_f32_e32 v65, v70, v70
	v_add_f32_e32 v64, v64, v65
	v_mul_f32_e32 v65, v75, v75
	v_mul_f32_e32 v66, v73, v73
	v_fmac_f32_e32 v65, v74, v74
	v_fmac_f32_e32 v66, v72, v72
	v_add_f32_e32 v65, v65, v66
	v_and_b32_e32 v66, 64, v164
	v_add_f32_e32 v64, v64, v65
	v_xor_b32_e32 v65, 16, v164
	v_add_u32_e32 v66, 64, v66
	v_cmp_lt_i32_e32 vcc, v65, v66
	v_add_f32_e32 v64, v82, v64
	s_nop 0
	v_cndmask_b32_e32 v65, v164, v65, vcc
	v_lshlrev_b32_e32 v65, 2, v65
	ds_bpermute_b32 v65, v65, v64
	s_waitcnt lgkmcnt(0)
	v_add_f32_e32 v64, v64, v65
	v_xor_b32_e32 v65, 32, v164
	v_cmp_lt_i32_e32 vcc, v65, v66
	s_nop 1
	v_cndmask_b32_e32 v65, v164, v65, vcc
	v_lshlrev_b32_e32 v65, 2, v65
	ds_bpermute_b32 v65, v65, v64
	s_and_b64 exec, exec, s[8:9]
	s_cbranch_execz .LBB0_806
	s_waitcnt lgkmcnt(0)
	v_add_f32_e32 v66, v64, v65
	v_lshlrev_b64 v[64:65], 7, v[80:81]
	s_lshl_b32 s14, s0, 2
	v_lshl_add_u64 v[64:65], s[16:17], 0, v[64:65]
	s_ashr_i32 s15, s14, 31
	v_lshl_add_u64 v[64:65], s[14:15], 2, v[64:65]
	s_lshl_b32 s14, s57, 2
	s_mov_b32 s15, s3
	v_lshl_add_u64 v[64:65], v[64:65], 0, s[14:15]
	flat_store_dword v[64:65], v66 sc1

.LBB0_1045:
	s_lshl_b32 s59, s57, 8
	v_or_b32_e32 v152, s59, v160
	s_cmp_gt_i32 s2, -1
	v_ashrrev_i32_e32 v153, 31, v152
	s_cbranch_scc1 .LBB0_1075
	s_lshl_b32 s14, s58, 8
	v_add_u32_e32 v154, s14, v138
	v_lshlrev_b32_e32 v180, 12, v154
	v_mov_b32_e32 v181, 0
	v_lshl_add_u64 v[180:181], s[6:7], 0, v[180:181]
	v_lshl_add_u64 v[180:181], v[152:153], 1, v[180:181]
	global_load_dwordx4 v[186:189], v[180:181], off
	global_load_dwordx4 v[190:193], v[180:181], off offset:256
	v_add_co_u32_e32 v180, vcc, 0x10000, v180
	s_nop 1
	v_addc_co_u32_e32 v181, vcc, 0, v181, vcc
	global_load_dwordx4 v[194:197], v[180:181], off
	global_load_dwordx4 v[198:201], v[180:181], off offset:256
	v_add_co_u32_e32 v180, vcc, 0x10000, v180
	s_nop 1
	v_addc_co_u32_e32 v181, vcc, 0, v181, vcc
	global_load_dwordx4 v[202:205], v[180:181], off
	global_load_dwordx4 v[206:209], v[180:181], off offset:256
	v_add_co_u32_e32 v180, vcc, 0x10000, v180
	s_nop 1
	v_addc_co_u32_e32 v181, vcc, 0, v181, vcc
	global_load_dwordx4 v[210:213], v[180:181], off
	global_load_dwordx4 v[214:217], v[180:181], off offset:256
	s_waitcnt vmcnt(0)
	v_cmp_gt_i32_e32 vcc, s87, v154
	s_and_saveexec_b64 s[0:1], vcc
	s_cbranch_execz .LBB0_1049
	v_ashrrev_i32_e32 v155, 31, v154
	v_lshlrev_b64 v[156:157], 12, v[154:155]
	v_lshl_add_u64 v[156:157], s[6:7], 0, v[156:157]
	v_lshl_add_u64 v[156:157], v[152:153], 1, v[156:157]
	v_mov_b64_e32 v[166:167], v[186:187]
	v_mov_b64_e32 v[168:169], v[188:189]
	v_lshlrev_b32_e32 v170, 16, v166
	v_and_b32_e32 v171, 0xffff0000, v166
	v_lshlrev_b32_e32 v166, 16, v167
	v_and_b32_e32 v167, 0xffff0000, v167
	v_pk_add_f32 v[174:175], v[62:63], v[166:167]
	v_pk_add_f32 v[170:171], v[60:61], v[170:171]
	v_lshlrev_b32_e32 v172, 16, v168
	v_and_b32_e32 v173, 0xffff0000, v168
	v_lshlrev_b32_e32 v168, 16, v169
	v_and_b32_e32 v169, 0xffff0000, v169
	v_mul_f32_e32 v136, v171, v171
	v_mul_f32_e32 v165, v175, v175
	v_pk_add_f32 v[176:177], v[58:59], v[168:169]
	v_pk_add_f32 v[172:173], v[56:57], v[172:173]
	s_nop 1
	v_cvt_pk_bf16_f32 v166, v170, v171
	v_fmac_f32_e32 v136, v170, v170
	v_fmac_f32_e32 v165, v174, v174
	s_nop 1
	v_cvt_pk_bf16_f32 v167, v174, v175
	s_nop 1
	v_cvt_pk_bf16_f32 v168, v172, v173
	s_nop 1
	v_cvt_pk_bf16_f32 v169, v176, v177
	global_store_dwordx4 v[156:157], v[166:169], off
	v_add_f32_e32 v136, v136, v165
	v_mul_f32_e32 v165, v173, v173
	v_mul_f32_e32 v166, v177, v177
	v_fmac_f32_e32 v165, v172, v172
	v_fmac_f32_e32 v166, v176, v176
	v_add_f32_e32 v165, v165, v166
	v_mov_b64_e32 v[166:167], v[190:191]
	v_mov_b64_e32 v[168:169], v[192:193]
	v_add_f32_e32 v136, v136, v165
	v_lshlrev_b32_e32 v170, 16, v166
	v_and_b32_e32 v171, 0xffff0000, v166
	v_lshlrev_b32_e32 v166, 16, v167
	v_and_b32_e32 v167, 0xffff0000, v167
	v_lshlrev_b32_e32 v172, 16, v168
	v_and_b32_e32 v173, 0xffff0000, v168
	v_lshlrev_b32_e32 v168, 16, v169
	v_and_b32_e32 v169, 0xffff0000, v169
	v_pk_add_f32 v[174:175], v[38:39], v[166:167]
	v_pk_add_f32 v[170:171], v[36:37], v[170:171]
	v_pk_add_f32 v[176:177], v[34:35], v[168:169]
	v_pk_add_f32 v[172:173], v[32:33], v[172:173]
	s_nop 1
	v_cvt_pk_bf16_f32 v166, v170, v171
	s_nop 1
	v_cvt_pk_bf16_f32 v167, v174, v175
	v_mul_f32_e32 v165, v177, v177
	s_nop 1
	v_cvt_pk_bf16_f32 v168, v172, v173
	s_nop 1
	v_cvt_pk_bf16_f32 v169, v176, v177
	global_store_dwordx4 v[156:157], v[166:169], off offset:256
	v_mul_f32_e32 v156, v171, v171
	v_mul_f32_e32 v157, v175, v175
	v_fmac_f32_e32 v156, v170, v170
	v_fmac_f32_e32 v157, v174, v174
	v_add_f32_e32 v156, v156, v157
	v_mul_f32_e32 v157, v173, v173
	v_fmac_f32_e32 v157, v172, v172
	v_fmac_f32_e32 v165, v176, v176
	v_add_f32_e32 v157, v157, v165
	v_add_f32_e32 v156, v156, v157
	v_and_b32_e32 v157, 64, v164
	v_add_f32_e32 v136, v136, v156
	v_xor_b32_e32 v156, 16, v164
	v_add_u32_e32 v157, 64, v157
	v_cmp_lt_i32_e32 vcc, v156, v157
	s_nop 1
	v_cndmask_b32_e32 v156, v164, v156, vcc
	v_lshlrev_b32_e32 v156, 2, v156
	ds_bpermute_b32 v156, v156, v136
	s_waitcnt lgkmcnt(0)
	v_add_f32_e32 v136, v136, v156
	v_xor_b32_e32 v156, 32, v164
	v_cmp_lt_i32_e32 vcc, v156, v157
	s_nop 1
	v_cndmask_b32_e32 v156, v164, v156, vcc
	v_lshlrev_b32_e32 v156, 2, v156
	ds_bpermute_b32 v156, v156, v136
	s_and_b64 exec, exec, s[10:11]
	s_cbranch_execz .LBB0_1049
	s_waitcnt lgkmcnt(0)
	v_add_f32_e32 v136, v136, v156
	v_lshlrev_b64 v[156:157], 7, v[154:155]
	s_lshl_b32 s8, s57, 2
	v_lshl_add_u64 v[156:157], s[26:27], 0, v[156:157]
	s_ashr_i32 s9, s8, 31
	v_lshl_add_u64 v[156:157], s[8:9], 2, v[156:157]
	s_lshl_b32 s8, s82, 2
	s_mov_b32 s9, s3
	v_lshl_add_u64 v[156:157], v[156:157], 0, s[8:9]
	flat_store_dword v[156:157], v136 sc1
.LBB0_1049:
	s_or_b64 exec, exec, s[0:1]
	s_waitcnt lgkmcnt(0)
	v_or_b32_e32 v156, 16, v154
	v_cmp_gt_i32_e32 vcc, s87, v156
	s_and_saveexec_b64 s[0:1], vcc
	s_cbranch_execz .LBB0_1052
	v_ashrrev_i32_e32 v157, 31, v156
	v_lshlrev_b64 v[166:167], 12, v[156:157]
	v_lshl_add_u64 v[166:167], s[6:7], 0, v[166:167]
	v_lshl_add_u64 v[170:171], v[152:153], 1, v[166:167]
	v_mov_b64_e32 v[166:167], v[194:195]
	v_mov_b64_e32 v[168:169], v[196:197]
	v_lshlrev_b32_e32 v172, 16, v168
	v_and_b32_e32 v173, 0xffff0000, v168
	v_lshlrev_b32_e32 v168, 16, v169
	v_and_b32_e32 v169, 0xffff0000, v169
	v_pk_add_f32 v[174:175], v[50:51], v[168:169]
	v_lshlrev_b32_e32 v168, 16, v166
	v_and_b32_e32 v169, 0xffff0000, v166
	v_lshlrev_b32_e32 v166, 16, v167
	v_and_b32_e32 v167, 0xffff0000, v167
	v_pk_add_f32 v[172:173], v[48:49], v[172:173]
	v_pk_add_f32 v[176:177], v[54:55], v[166:167]
	v_pk_add_f32 v[178:179], v[52:53], v[168:169]
	v_mul_f32_e32 v155, v177, v177
	s_nop 1
	v_cvt_pk_bf16_f32 v166, v178, v179
	s_nop 1
	v_cvt_pk_bf16_f32 v167, v176, v177
	s_nop 1
	v_cvt_pk_bf16_f32 v168, v172, v173
	s_nop 1
	v_cvt_pk_bf16_f32 v169, v174, v175
	global_store_dwordx4 v[170:171], v[166:169], off
	s_nop 1
	v_mov_b64_e32 v[166:167], v[198:199]
	v_mov_b64_e32 v[168:169], v[200:201]
	v_mul_f32_e32 v136, v179, v179
	v_fmac_f32_e32 v136, v178, v178
	v_fmac_f32_e32 v155, v176, v176
	v_add_f32_e32 v136, v136, v155
	v_mul_f32_e32 v155, v173, v173
	v_mul_f32_e32 v165, v175, v175
	v_fmac_f32_e32 v155, v172, v172
	v_fmac_f32_e32 v165, v174, v174
	v_add_f32_e32 v155, v155, v165
	v_add_f32_e32 v136, v136, v155
	v_lshlrev_b32_e32 v172, 16, v166
	v_and_b32_e32 v173, 0xffff0000, v166
	v_lshlrev_b32_e32 v166, 16, v167
	v_and_b32_e32 v167, 0xffff0000, v167
	v_pk_add_f32 v[176:177], v[22:23], v[166:167]
	v_pk_add_f32 v[172:173], v[20:21], v[172:173]
	v_lshlrev_b32_e32 v174, 16, v168
	v_and_b32_e32 v175, 0xffff0000, v168
	v_lshlrev_b32_e32 v168, 16, v169
	v_and_b32_e32 v169, 0xffff0000, v169
	v_mul_f32_e32 v155, v173, v173
	v_mul_f32_e32 v165, v177, v177
	v_pk_add_f32 v[178:179], v[18:19], v[168:169]
	v_pk_add_f32 v[174:175], v[16:17], v[174:175]
	s_nop 1
	v_cvt_pk_bf16_f32 v166, v172, v173
	v_fmac_f32_e32 v155, v172, v172
	v_fmac_f32_e32 v165, v176, v176
	s_nop 1
	v_cvt_pk_bf16_f32 v167, v176, v177
	s_nop 1
	v_cvt_pk_bf16_f32 v168, v174, v175
	s_nop 1
	v_cvt_pk_bf16_f32 v169, v178, v179
	global_store_dwordx4 v[170:171], v[166:169], off offset:256
	v_add_f32_e32 v155, v155, v165
	v_mul_f32_e32 v165, v175, v175
	v_mul_f32_e32 v166, v179, v179
	v_fmac_f32_e32 v165, v174, v174
	v_fmac_f32_e32 v166, v178, v178
	v_add_f32_e32 v165, v165, v166
	v_add_f32_e32 v155, v155, v165
	v_and_b32_e32 v165, 64, v164
	v_add_f32_e32 v136, v136, v155
	v_xor_b32_e32 v155, 16, v164
	v_add_u32_e32 v165, 64, v165
	v_cmp_lt_i32_e32 vcc, v155, v165
	s_nop 1
	v_cndmask_b32_e32 v155, v164, v155, vcc
	v_lshlrev_b32_e32 v155, 2, v155
	ds_bpermute_b32 v155, v155, v136
	s_waitcnt lgkmcnt(0)
	v_add_f32_e32 v136, v136, v155
	v_xor_b32_e32 v155, 32, v164
	v_cmp_lt_i32_e32 vcc, v155, v165
	s_nop 1
	v_cndmask_b32_e32 v155, v164, v155, vcc
	v_lshlrev_b32_e32 v155, 2, v155
	ds_bpermute_b32 v155, v155, v136
	s_and_b64 exec, exec, s[10:11]
	s_cbranch_execz .LBB0_1052
	v_lshlrev_b64 v[156:157], 7, v[156:157]
	s_lshl_b32 s8, s57, 2
	v_lshl_add_u64 v[156:157], s[26:27], 0, v[156:157]
	s_ashr_i32 s9, s8, 31
	v_lshl_add_u64 v[156:157], s[8:9], 2, v[156:157]
	s_lshl_b32 s8, s82, 2
	s_mov_b32 s9, s3
	s_waitcnt lgkmcnt(0)
	v_add_f32_e32 v136, v136, v155
	v_lshl_add_u64 v[156:157], v[156:157], 0, s[8:9]
	flat_store_dword v[156:157], v136 sc1
.LBB0_1052:
	s_or_b64 exec, exec, s[0:1]
	v_or_b32_e32 v156, 32, v154
	v_cmp_gt_i32_e32 vcc, s87, v156
	s_and_saveexec_b64 s[0:1], vcc
	s_cbranch_execz .LBB0_1055
	v_ashrrev_i32_e32 v157, 31, v156
	v_lshlrev_b64 v[166:167], 12, v[156:157]
	v_lshl_add_u64 v[166:167], s[6:7], 0, v[166:167]
	v_lshl_add_u64 v[170:171], v[152:153], 1, v[166:167]
	v_mov_b64_e32 v[166:167], v[202:203]
	v_mov_b64_e32 v[168:169], v[204:205]
	v_lshlrev_b32_e32 v172, 16, v168
	v_and_b32_e32 v173, 0xffff0000, v168
	v_lshlrev_b32_e32 v168, 16, v169
	v_and_b32_e32 v169, 0xffff0000, v169
	v_pk_add_f32 v[174:175], v[42:43], v[168:169]
	v_lshlrev_b32_e32 v168, 16, v166
	v_and_b32_e32 v169, 0xffff0000, v166
	v_lshlrev_b32_e32 v166, 16, v167
	v_and_b32_e32 v167, 0xffff0000, v167
	v_pk_add_f32 v[172:173], v[40:41], v[172:173]
	v_pk_add_f32 v[176:177], v[46:47], v[166:167]
	v_pk_add_f32 v[178:179], v[44:45], v[168:169]
	s_waitcnt lgkmcnt(0)
	v_mul_f32_e32 v155, v177, v177
	s_nop 1
	v_cvt_pk_bf16_f32 v166, v178, v179
	s_nop 1
	v_cvt_pk_bf16_f32 v167, v176, v177
	s_nop 1
	v_cvt_pk_bf16_f32 v168, v172, v173
	s_nop 1
	v_cvt_pk_bf16_f32 v169, v174, v175
	global_store_dwordx4 v[170:171], v[166:169], off
	s_nop 1
	v_mov_b64_e32 v[166:167], v[206:207]
	v_mov_b64_e32 v[168:169], v[208:209]
	v_mul_f32_e32 v136, v179, v179
	v_fmac_f32_e32 v136, v178, v178
	v_fmac_f32_e32 v155, v176, v176
	v_add_f32_e32 v136, v136, v155
	v_mul_f32_e32 v155, v173, v173
	v_mul_f32_e32 v165, v175, v175
	v_fmac_f32_e32 v155, v172, v172
	v_fmac_f32_e32 v165, v174, v174
	v_add_f32_e32 v155, v155, v165
	v_add_f32_e32 v136, v136, v155
	v_lshlrev_b32_e32 v172, 16, v166
	v_and_b32_e32 v173, 0xffff0000, v166
	v_lshlrev_b32_e32 v166, 16, v167
	v_and_b32_e32 v167, 0xffff0000, v167
	v_pk_add_f32 v[176:177], v[14:15], v[166:167]
	v_pk_add_f32 v[172:173], v[12:13], v[172:173]
	v_lshlrev_b32_e32 v174, 16, v168
	v_and_b32_e32 v175, 0xffff0000, v168
	v_lshlrev_b32_e32 v168, 16, v169
	v_and_b32_e32 v169, 0xffff0000, v169
	v_mul_f32_e32 v155, v173, v173
	v_mul_f32_e32 v165, v177, v177
	v_pk_add_f32 v[178:179], v[10:11], v[168:169]
	v_pk_add_f32 v[174:175], v[8:9], v[174:175]
	s_nop 1
	v_cvt_pk_bf16_f32 v166, v172, v173
	v_fmac_f32_e32 v155, v172, v172
	v_fmac_f32_e32 v165, v176, v176
	s_nop 1
	v_cvt_pk_bf16_f32 v167, v176, v177
	s_nop 1
	v_cvt_pk_bf16_f32 v168, v174, v175
	s_nop 1
	v_cvt_pk_bf16_f32 v169, v178, v179
	global_store_dwordx4 v[170:171], v[166:169], off offset:256
	v_add_f32_e32 v155, v155, v165
	v_mul_f32_e32 v165, v175, v175
	v_mul_f32_e32 v166, v179, v179
	v_fmac_f32_e32 v165, v174, v174
	v_fmac_f32_e32 v166, v178, v178
	v_add_f32_e32 v165, v165, v166
	v_add_f32_e32 v155, v155, v165
	v_and_b32_e32 v165, 64, v164
	v_add_f32_e32 v136, v136, v155
	v_xor_b32_e32 v155, 16, v164
	v_add_u32_e32 v165, 64, v165
	v_cmp_lt_i32_e32 vcc, v155, v165
	s_nop 1
	v_cndmask_b32_e32 v155, v164, v155, vcc
	v_lshlrev_b32_e32 v155, 2, v155
	ds_bpermute_b32 v155, v155, v136
	s_waitcnt lgkmcnt(0)
	v_add_f32_e32 v136, v136, v155
	v_xor_b32_e32 v155, 32, v164
	v_cmp_lt_i32_e32 vcc, v155, v165
	s_nop 1
	v_cndmask_b32_e32 v155, v164, v155, vcc
	v_lshlrev_b32_e32 v155, 2, v155
	ds_bpermute_b32 v155, v155, v136
	s_and_b64 exec, exec, s[10:11]
	s_cbranch_execz .LBB0_1055
	v_lshlrev_b64 v[156:157], 7, v[156:157]
	s_lshl_b32 s8, s57, 2
	v_lshl_add_u64 v[156:157], s[26:27], 0, v[156:157]
	s_ashr_i32 s9, s8, 31
	v_lshl_add_u64 v[156:157], s[8:9], 2, v[156:157]
	s_lshl_b32 s8, s82, 2
	s_mov_b32 s9, s3
	s_waitcnt lgkmcnt(0)
	v_add_f32_e32 v136, v136, v155
	v_lshl_add_u64 v[156:157], v[156:157], 0, s[8:9]
	flat_store_dword v[156:157], v136 sc1
.LBB0_1055:
	s_or_b64 exec, exec, s[0:1]
	v_or_b32_e32 v156, 48, v154
	v_cmp_gt_i32_e32 vcc, s87, v156
	s_and_saveexec_b64 s[0:1], vcc
	s_cbranch_execz .LBB0_1058
	v_ashrrev_i32_e32 v157, 31, v156
	v_lshlrev_b64 v[166:167], 12, v[156:157]
	v_lshl_add_u64 v[166:167], s[6:7], 0, v[166:167]
	v_lshl_add_u64 v[170:171], v[152:153], 1, v[166:167]
	v_mov_b64_e32 v[166:167], v[210:211]
	v_mov_b64_e32 v[168:169], v[212:213]
	v_lshlrev_b32_e32 v172, 16, v168
	v_and_b32_e32 v173, 0xffff0000, v168
	v_lshlrev_b32_e32 v168, 16, v169
	v_and_b32_e32 v169, 0xffff0000, v169
	v_pk_add_f32 v[174:175], v[26:27], v[168:169]
	v_lshlrev_b32_e32 v168, 16, v166
	v_and_b32_e32 v169, 0xffff0000, v166
	v_lshlrev_b32_e32 v166, 16, v167
	v_and_b32_e32 v167, 0xffff0000, v167
	v_pk_add_f32 v[172:173], v[24:25], v[172:173]
	v_pk_add_f32 v[176:177], v[30:31], v[166:167]
	v_pk_add_f32 v[178:179], v[28:29], v[168:169]
	s_waitcnt lgkmcnt(0)
	v_mul_f32_e32 v155, v177, v177
	s_nop 1
	v_cvt_pk_bf16_f32 v166, v178, v179
	s_nop 1
	v_cvt_pk_bf16_f32 v167, v176, v177
	s_nop 1
	v_cvt_pk_bf16_f32 v168, v172, v173
	s_nop 1
	v_cvt_pk_bf16_f32 v169, v174, v175
	global_store_dwordx4 v[170:171], v[166:169], off
	s_nop 1
	v_mov_b64_e32 v[166:167], v[214:215]
	v_mov_b64_e32 v[168:169], v[216:217]
	v_mul_f32_e32 v136, v179, v179
	v_fmac_f32_e32 v136, v178, v178
	v_fmac_f32_e32 v155, v176, v176
	v_add_f32_e32 v136, v136, v155
	v_mul_f32_e32 v155, v173, v173
	v_mul_f32_e32 v165, v175, v175
	v_fmac_f32_e32 v155, v172, v172
	v_fmac_f32_e32 v165, v174, v174
	v_add_f32_e32 v155, v155, v165
	v_add_f32_e32 v136, v136, v155
	v_lshlrev_b32_e32 v172, 16, v166
	v_and_b32_e32 v173, 0xffff0000, v166
	v_lshlrev_b32_e32 v166, 16, v167
	v_and_b32_e32 v167, 0xffff0000, v167
	v_pk_add_f32 v[176:177], v[6:7], v[166:167]
	v_pk_add_f32 v[172:173], v[4:5], v[172:173]
	v_lshlrev_b32_e32 v174, 16, v168
	v_and_b32_e32 v175, 0xffff0000, v168
	v_lshlrev_b32_e32 v168, 16, v169
	v_and_b32_e32 v169, 0xffff0000, v169
	v_mul_f32_e32 v155, v173, v173
	v_mul_f32_e32 v165, v177, v177
	v_pk_add_f32 v[178:179], v[2:3], v[168:169]
	v_pk_add_f32 v[174:175], v[0:1], v[174:175]
	s_nop 1
	v_cvt_pk_bf16_f32 v166, v172, v173
	v_fmac_f32_e32 v155, v172, v172
	v_fmac_f32_e32 v165, v176, v176
	s_nop 1
	v_cvt_pk_bf16_f32 v167, v176, v177
	s_nop 1
	v_cvt_pk_bf16_f32 v168, v174, v175
	s_nop 1
	v_cvt_pk_bf16_f32 v169, v178, v179
	global_store_dwordx4 v[170:171], v[166:169], off offset:256
	v_add_f32_e32 v155, v155, v165
	v_mul_f32_e32 v165, v175, v175
	v_mul_f32_e32 v166, v179, v179
	v_fmac_f32_e32 v165, v174, v174
	v_fmac_f32_e32 v166, v178, v178
	v_add_f32_e32 v165, v165, v166
	v_add_f32_e32 v155, v155, v165
	v_and_b32_e32 v165, 64, v164
	v_add_f32_e32 v136, v136, v155
	v_xor_b32_e32 v155, 16, v164
	v_add_u32_e32 v165, 64, v165
	v_cmp_lt_i32_e32 vcc, v155, v165
	s_nop 1
	v_cndmask_b32_e32 v155, v164, v155, vcc
	v_lshlrev_b32_e32 v155, 2, v155
	ds_bpermute_b32 v155, v155, v136
	s_waitcnt lgkmcnt(0)
	v_add_f32_e32 v136, v136, v155
	v_xor_b32_e32 v155, 32, v164
	v_cmp_lt_i32_e32 vcc, v155, v165
	s_nop 1
	v_cndmask_b32_e32 v155, v164, v155, vcc
	v_lshlrev_b32_e32 v155, 2, v155
	ds_bpermute_b32 v155, v155, v136
	s_and_b64 exec, exec, s[10:11]
	s_cbranch_execz .LBB0_1058
	v_lshlrev_b64 v[156:157], 7, v[156:157]
	s_lshl_b32 s8, s57, 2
	v_lshl_add_u64 v[156:157], s[26:27], 0, v[156:157]
	s_ashr_i32 s9, s8, 31
	v_lshl_add_u64 v[156:157], s[8:9], 2, v[156:157]
	s_lshl_b32 s8, s82, 2
	s_mov_b32 s9, s3
	s_waitcnt lgkmcnt(0)
	v_add_f32_e32 v136, v136, v155
	v_lshl_add_u64 v[156:157], v[156:157], 0, s[8:9]
	flat_store_dword v[156:157], v136 sc1
.LBB0_1058:
	s_or_b64 exec, exec, s[0:1]
	s_movk_i32 s0, 0x2080
	v_lshlrev_b32_e32 v180, 12, v154
	v_mov_b32_e32 v181, 0
	v_lshl_add_u64 v[180:181], s[6:7], 0, v[180:181]
	v_lshl_add_u64 v[180:181], v[152:153], 1, v[180:181]
	v_add_co_u32_e32 v180, vcc, 0x80000, v180
	s_nop 1
	v_addc_co_u32_e32 v181, vcc, 0, v181, vcc
	global_load_dwordx4 v[186:189], v[180:181], off
	global_load_dwordx4 v[190:193], v[180:181], off offset:256
	v_add_co_u32_e32 v180, vcc, 0x10000, v180
	s_nop 1
	v_addc_co_u32_e32 v181, vcc, 0, v181, vcc
	global_load_dwordx4 v[194:197], v[180:181], off
	global_load_dwordx4 v[198:201], v[180:181], off offset:256
	v_add_co_u32_e32 v180, vcc, 0x10000, v180
	s_nop 1
	v_addc_co_u32_e32 v181, vcc, 0, v181, vcc
	global_load_dwordx4 v[202:205], v[180:181], off
	global_load_dwordx4 v[206:209], v[180:181], off offset:256
	v_add_co_u32_e32 v180, vcc, 0x10000, v180
	s_nop 1
	v_addc_co_u32_e32 v181, vcc, 0, v181, vcc
	global_load_dwordx4 v[210:213], v[180:181], off
	global_load_dwordx4 v[214:217], v[180:181], off offset:256
	s_waitcnt vmcnt(0)
	v_cmp_gt_i32_e32 vcc, s0, v154
	s_and_saveexec_b64 s[0:1], vcc
	s_cbranch_execz .LBB0_1061
	v_add_u32_e32 v156, 0x80, v154
	v_ashrrev_i32_e32 v157, 31, v156
	v_lshlrev_b64 v[166:167], 12, v[156:157]
	v_lshl_add_u64 v[166:167], s[6:7], 0, v[166:167]
	v_lshl_add_u64 v[170:171], v[152:153], 1, v[166:167]
	v_mov_b64_e32 v[166:167], v[186:187]
	v_mov_b64_e32 v[168:169], v[188:189]
	v_lshlrev_b32_e32 v172, 16, v168
	v_and_b32_e32 v173, 0xffff0000, v168
	v_lshlrev_b32_e32 v168, 16, v169
	v_and_b32_e32 v169, 0xffff0000, v169
	v_pk_add_f32 v[126:127], v[126:127], v[168:169]
	v_lshlrev_b32_e32 v168, 16, v166
	v_and_b32_e32 v169, 0xffff0000, v166
	v_lshlrev_b32_e32 v166, 16, v167
	v_and_b32_e32 v167, 0xffff0000, v167
	v_pk_add_f32 v[166:167], v[122:123], v[166:167]
	v_pk_add_f32 v[168:169], v[120:121], v[168:169]
	v_pk_add_f32 v[124:125], v[124:125], v[172:173]
	s_nop 1
	v_cvt_pk_bf16_f32 v120, v168, v169
	s_nop 1
	v_cvt_pk_bf16_f32 v121, v166, v167
	s_nop 0
	s_nop 1
	v_cvt_pk_bf16_f32 v122, v124, v125
	s_nop 1
	v_cvt_pk_bf16_f32 v123, v126, v127
	global_store_dwordx4 v[170:171], v[120:123], off
	s_nop 1
	v_mul_f32_e32 v120, v169, v169
	v_mul_f32_e32 v121, v167, v167
	v_fmac_f32_e32 v120, v168, v168
	v_fmac_f32_e32 v121, v166, v166
	v_add_f32_e32 v120, v120, v121
	v_mul_f32_e32 v121, v125, v125
	v_mul_f32_e32 v122, v127, v127
	v_fmac_f32_e32 v121, v124, v124
	v_fmac_f32_e32 v122, v126, v126
	v_add_f32_e32 v121, v121, v122
	v_add_f32_e32 v136, v120, v121
	v_mov_b64_e32 v[120:121], v[190:191]
	v_mov_b64_e32 v[122:123], v[192:193]
	v_lshlrev_b32_e32 v124, 16, v120
	v_and_b32_e32 v125, 0xffff0000, v120
	v_lshlrev_b32_e32 v120, 16, v121
	v_and_b32_e32 v121, 0xffff0000, v121
	v_lshlrev_b32_e32 v126, 16, v122
	v_and_b32_e32 v127, 0xffff0000, v122
	v_lshlrev_b32_e32 v122, 16, v123
	v_and_b32_e32 v123, 0xffff0000, v123
	v_pk_add_f32 v[118:119], v[118:119], v[120:121]
	v_pk_add_f32 v[116:117], v[116:117], v[124:125]
	v_pk_add_f32 v[120:121], v[114:115], v[122:123]
	v_pk_add_f32 v[122:123], v[112:113], v[126:127]
	s_nop 1
	v_cvt_pk_bf16_f32 v112, v116, v117
	s_nop 1
	v_cvt_pk_bf16_f32 v113, v118, v119
	s_nop 0
	s_nop 1
	v_cvt_pk_bf16_f32 v114, v122, v123
	s_nop 1
	v_cvt_pk_bf16_f32 v115, v120, v121
	global_store_dwordx4 v[170:171], v[112:115], off offset:256
	s_nop 1
	v_mul_f32_e32 v112, v117, v117
	v_mul_f32_e32 v113, v119, v119
	v_fmac_f32_e32 v112, v116, v116
	v_fmac_f32_e32 v113, v118, v118
	v_add_f32_e32 v112, v112, v113
	v_mul_f32_e32 v113, v123, v123
	v_mul_f32_e32 v114, v121, v121
	v_fmac_f32_e32 v113, v122, v122
	v_fmac_f32_e32 v114, v120, v120
	v_add_f32_e32 v113, v113, v114
	v_and_b32_e32 v114, 64, v164
	v_add_f32_e32 v112, v112, v113
	v_xor_b32_e32 v113, 16, v164
	v_add_u32_e32 v114, 64, v114
	v_cmp_lt_i32_e32 vcc, v113, v114
	v_add_f32_e32 v112, v136, v112
	s_nop 0
	v_cndmask_b32_e32 v113, v164, v113, vcc
	v_lshlrev_b32_e32 v113, 2, v113
	ds_bpermute_b32 v113, v113, v112
	s_waitcnt lgkmcnt(0)
	v_add_f32_e32 v112, v112, v113
	v_xor_b32_e32 v113, 32, v164
	v_cmp_lt_i32_e32 vcc, v113, v114
	s_nop 1
	v_cndmask_b32_e32 v113, v164, v113, vcc
	v_lshlrev_b32_e32 v113, 2, v113
	ds_bpermute_b32 v113, v113, v112
	s_and_b64 exec, exec, s[10:11]
	s_cbranch_execz .LBB0_1061
	s_waitcnt lgkmcnt(0)
	v_add_f32_e32 v114, v112, v113
	v_lshlrev_b64 v[112:113], 7, v[156:157]
	s_lshl_b32 s8, s57, 2
	v_lshl_add_u64 v[112:113], s[26:27], 0, v[112:113]
	s_ashr_i32 s9, s8, 31
	v_lshl_add_u64 v[112:113], s[8:9], 2, v[112:113]
	s_lshl_b32 s8, s82, 2
	s_mov_b32 s9, s3
	v_lshl_add_u64 v[112:113], v[112:113], 0, s[8:9]
	flat_store_dword v[112:113], v114 sc1
.LBB0_1061:
	s_or_b64 exec, exec, s[0:1]
	s_movk_i32 s0, 0x2070
	v_cmp_gt_i32_e32 vcc, s0, v154
	s_and_saveexec_b64 s[0:1], vcc
	s_cbranch_execz .LBB0_1064
	v_add_u32_e32 v112, 0x90, v154
	s_waitcnt lgkmcnt(0)
	v_ashrrev_i32_e32 v113, 31, v112
	v_lshlrev_b64 v[114:115], 12, v[112:113]
	v_lshl_add_u64 v[114:115], s[6:7], 0, v[114:115]
	v_lshl_add_u64 v[118:119], v[152:153], 1, v[114:115]
	v_mov_b64_e32 v[114:115], v[194:195]
	v_mov_b64_e32 v[116:117], v[196:197]
	v_lshlrev_b32_e32 v120, 16, v116
	v_and_b32_e32 v121, 0xffff0000, v116
	v_lshlrev_b32_e32 v116, 16, v117
	v_and_b32_e32 v117, 0xffff0000, v117
	v_pk_add_f32 v[110:111], v[110:111], v[116:117]
	v_lshlrev_b32_e32 v116, 16, v114
	v_and_b32_e32 v117, 0xffff0000, v114
	v_lshlrev_b32_e32 v114, 16, v115
	v_and_b32_e32 v115, 0xffff0000, v115
	v_pk_add_f32 v[114:115], v[106:107], v[114:115]
	v_pk_add_f32 v[116:117], v[104:105], v[116:117]
	v_pk_add_f32 v[108:109], v[108:109], v[120:121]
	s_nop 1
	v_cvt_pk_bf16_f32 v104, v116, v117
	s_nop 1
	v_cvt_pk_bf16_f32 v105, v114, v115
	s_nop 0
	s_nop 1
	v_cvt_pk_bf16_f32 v106, v108, v109
	s_nop 1
	v_cvt_pk_bf16_f32 v107, v110, v111
	global_store_dwordx4 v[118:119], v[104:107], off
	s_nop 1
	v_mul_f32_e32 v104, v117, v117
	v_mul_f32_e32 v105, v115, v115
	v_fmac_f32_e32 v104, v116, v116
	v_fmac_f32_e32 v105, v114, v114
	v_add_f32_e32 v104, v104, v105
	v_mul_f32_e32 v105, v109, v109
	v_mul_f32_e32 v106, v111, v111
	v_fmac_f32_e32 v105, v108, v108
	v_fmac_f32_e32 v106, v110, v110
	v_add_f32_e32 v105, v105, v106
	v_add_f32_e32 v114, v104, v105
	v_mov_b64_e32 v[104:105], v[198:199]
	v_mov_b64_e32 v[106:107], v[200:201]
	v_lshlrev_b32_e32 v108, 16, v104
	v_and_b32_e32 v109, 0xffff0000, v104
	v_lshlrev_b32_e32 v104, 16, v105
	v_and_b32_e32 v105, 0xffff0000, v105
	v_lshlrev_b32_e32 v110, 16, v106
	v_and_b32_e32 v111, 0xffff0000, v106
	v_lshlrev_b32_e32 v106, 16, v107
	v_and_b32_e32 v107, 0xffff0000, v107
	v_pk_add_f32 v[102:103], v[102:103], v[104:105]
	v_pk_add_f32 v[100:101], v[100:101], v[108:109]
	v_pk_add_f32 v[104:105], v[98:99], v[106:107]
	v_pk_add_f32 v[106:107], v[96:97], v[110:111]
	s_nop 1
	v_cvt_pk_bf16_f32 v96, v100, v101
	s_nop 1
	v_cvt_pk_bf16_f32 v97, v102, v103
	s_nop 0
	s_nop 1
	v_cvt_pk_bf16_f32 v98, v106, v107
	s_nop 1
	v_cvt_pk_bf16_f32 v99, v104, v105
	global_store_dwordx4 v[118:119], v[96:99], off offset:256
	s_nop 1
	v_mul_f32_e32 v96, v101, v101
	v_mul_f32_e32 v97, v103, v103
	v_fmac_f32_e32 v96, v100, v100
	v_fmac_f32_e32 v97, v102, v102
	v_add_f32_e32 v96, v96, v97
	v_mul_f32_e32 v97, v107, v107
	v_mul_f32_e32 v98, v105, v105
	v_fmac_f32_e32 v97, v106, v106
	v_fmac_f32_e32 v98, v104, v104
	v_add_f32_e32 v97, v97, v98
	v_and_b32_e32 v98, 64, v164
	v_add_f32_e32 v96, v96, v97
	v_xor_b32_e32 v97, 16, v164
	v_add_u32_e32 v98, 64, v98
	v_cmp_lt_i32_e32 vcc, v97, v98
	v_add_f32_e32 v96, v114, v96
	s_nop 0
	v_cndmask_b32_e32 v97, v164, v97, vcc
	v_lshlrev_b32_e32 v97, 2, v97
	ds_bpermute_b32 v97, v97, v96
	s_waitcnt lgkmcnt(0)
	v_add_f32_e32 v96, v96, v97
	v_xor_b32_e32 v97, 32, v164
	v_cmp_lt_i32_e32 vcc, v97, v98
	s_nop 1
	v_cndmask_b32_e32 v97, v164, v97, vcc
	v_lshlrev_b32_e32 v97, 2, v97
	ds_bpermute_b32 v97, v97, v96
	s_and_b64 exec, exec, s[10:11]
	s_cbranch_execz .LBB0_1064
	s_waitcnt lgkmcnt(0)
	v_add_f32_e32 v98, v96, v97
	v_lshlrev_b64 v[96:97], 7, v[112:113]
	s_lshl_b32 s8, s57, 2
	v_lshl_add_u64 v[96:97], s[26:27], 0, v[96:97]
	s_ashr_i32 s9, s8, 31
	v_lshl_add_u64 v[96:97], s[8:9], 2, v[96:97]
	s_lshl_b32 s8, s82, 2
	s_mov_b32 s9, s3
	v_lshl_add_u64 v[96:97], v[96:97], 0, s[8:9]
	flat_store_dword v[96:97], v98 sc1
.LBB0_1064:
	s_or_b64 exec, exec, s[0:1]
	s_movk_i32 s0, 0x2060
	v_cmp_gt_i32_e32 vcc, s0, v154
	s_and_saveexec_b64 s[0:1], vcc
	s_cbranch_execz .LBB0_1067
	v_add_u32_e32 v96, 0xa0, v154
	s_waitcnt lgkmcnt(0)
	v_ashrrev_i32_e32 v97, 31, v96
	v_lshlrev_b64 v[98:99], 12, v[96:97]
	v_lshl_add_u64 v[98:99], s[6:7], 0, v[98:99]
	v_lshl_add_u64 v[102:103], v[152:153], 1, v[98:99]
	v_mov_b64_e32 v[98:99], v[202:203]
	v_mov_b64_e32 v[100:101], v[204:205]
	v_lshlrev_b32_e32 v104, 16, v100
	v_and_b32_e32 v105, 0xffff0000, v100
	v_lshlrev_b32_e32 v100, 16, v101
	v_and_b32_e32 v101, 0xffff0000, v101
	v_pk_add_f32 v[94:95], v[94:95], v[100:101]
	v_lshlrev_b32_e32 v100, 16, v98
	v_and_b32_e32 v101, 0xffff0000, v98
	v_lshlrev_b32_e32 v98, 16, v99
	v_and_b32_e32 v99, 0xffff0000, v99
	v_pk_add_f32 v[98:99], v[90:91], v[98:99]
	v_pk_add_f32 v[100:101], v[88:89], v[100:101]
	v_pk_add_f32 v[92:93], v[92:93], v[104:105]
	s_nop 1
	v_cvt_pk_bf16_f32 v88, v100, v101
	s_nop 1
	v_cvt_pk_bf16_f32 v89, v98, v99
	s_nop 0
	s_nop 1
	v_cvt_pk_bf16_f32 v90, v92, v93
	s_nop 1
	v_cvt_pk_bf16_f32 v91, v94, v95
	global_store_dwordx4 v[102:103], v[88:91], off
	s_nop 1
	v_mul_f32_e32 v88, v101, v101
	v_mul_f32_e32 v89, v99, v99
	v_fmac_f32_e32 v88, v100, v100
	v_fmac_f32_e32 v89, v98, v98
	v_add_f32_e32 v88, v88, v89
	v_mul_f32_e32 v89, v93, v93
	v_mul_f32_e32 v90, v95, v95
	v_fmac_f32_e32 v89, v92, v92
	v_fmac_f32_e32 v90, v94, v94
	v_add_f32_e32 v89, v89, v90
	v_add_f32_e32 v98, v88, v89
	v_mov_b64_e32 v[88:89], v[206:207]
	v_mov_b64_e32 v[90:91], v[208:209]
	v_lshlrev_b32_e32 v92, 16, v88
	v_and_b32_e32 v93, 0xffff0000, v88
	v_lshlrev_b32_e32 v88, 16, v89
	v_and_b32_e32 v89, 0xffff0000, v89
	v_lshlrev_b32_e32 v94, 16, v90
	v_and_b32_e32 v95, 0xffff0000, v90
	v_lshlrev_b32_e32 v90, 16, v91
	v_and_b32_e32 v91, 0xffff0000, v91
	v_pk_add_f32 v[86:87], v[86:87], v[88:89]
	v_pk_add_f32 v[84:85], v[84:85], v[92:93]
	v_pk_add_f32 v[88:89], v[82:83], v[90:91]
	v_pk_add_f32 v[90:91], v[80:81], v[94:95]
	s_nop 1
	v_cvt_pk_bf16_f32 v80, v84, v85
	s_nop 1
	v_cvt_pk_bf16_f32 v81, v86, v87
	s_nop 0
	s_nop 1
	v_cvt_pk_bf16_f32 v82, v90, v91
	s_nop 1
	v_cvt_pk_bf16_f32 v83, v88, v89
	global_store_dwordx4 v[102:103], v[80:83], off offset:256
	s_nop 1
	v_mul_f32_e32 v80, v85, v85
	v_mul_f32_e32 v81, v87, v87
	v_fmac_f32_e32 v80, v84, v84
	v_fmac_f32_e32 v81, v86, v86
	v_add_f32_e32 v80, v80, v81
	v_mul_f32_e32 v81, v91, v91
	v_mul_f32_e32 v82, v89, v89
	v_fmac_f32_e32 v81, v90, v90
	v_fmac_f32_e32 v82, v88, v88
	v_add_f32_e32 v81, v81, v82
	v_and_b32_e32 v82, 64, v164
	v_add_f32_e32 v80, v80, v81
	v_xor_b32_e32 v81, 16, v164
	v_add_u32_e32 v82, 64, v82
	v_cmp_lt_i32_e32 vcc, v81, v82
	v_add_f32_e32 v80, v98, v80
	s_nop 0
	v_cndmask_b32_e32 v81, v164, v81, vcc
	v_lshlrev_b32_e32 v81, 2, v81
	ds_bpermute_b32 v81, v81, v80
	s_waitcnt lgkmcnt(0)
	v_add_f32_e32 v80, v80, v81
	v_xor_b32_e32 v81, 32, v164
	v_cmp_lt_i32_e32 vcc, v81, v82
	s_nop 1
	v_cndmask_b32_e32 v81, v164, v81, vcc
	v_lshlrev_b32_e32 v81, 2, v81
	ds_bpermute_b32 v81, v81, v80
	s_and_b64 exec, exec, s[10:11]
	s_cbranch_execz .LBB0_1067
	s_waitcnt lgkmcnt(0)
	v_add_f32_e32 v82, v80, v81
	v_lshlrev_b64 v[80:81], 7, v[96:97]
	s_lshl_b32 s8, s57, 2
	v_lshl_add_u64 v[80:81], s[26:27], 0, v[80:81]
	s_ashr_i32 s9, s8, 31
	v_lshl_add_u64 v[80:81], s[8:9], 2, v[80:81]
	s_lshl_b32 s8, s82, 2
	s_mov_b32 s9, s3
	v_lshl_add_u64 v[80:81], v[80:81], 0, s[8:9]
	flat_store_dword v[80:81], v82 sc1
.LBB0_1067:
	s_or_b64 exec, exec, s[0:1]
	s_movk_i32 s0, 0x2050
	v_cmp_gt_i32_e32 vcc, s0, v154
	s_and_saveexec_b64 s[0:1], vcc
	s_cbranch_execz .LBB0_1070
	v_add_u32_e32 v80, 0xb0, v154
	s_waitcnt lgkmcnt(0)
	v_ashrrev_i32_e32 v81, 31, v80
	v_lshlrev_b64 v[82:83], 12, v[80:81]
	v_lshl_add_u64 v[82:83], s[6:7], 0, v[82:83]
	v_lshl_add_u64 v[86:87], v[152:153], 1, v[82:83]
	v_mov_b64_e32 v[82:83], v[210:211]
	v_mov_b64_e32 v[84:85], v[212:213]
	v_lshlrev_b32_e32 v88, 16, v84
	v_and_b32_e32 v89, 0xffff0000, v84
	v_lshlrev_b32_e32 v84, 16, v85
	v_and_b32_e32 v85, 0xffff0000, v85
	v_pk_add_f32 v[78:79], v[78:79], v[84:85]
	v_lshlrev_b32_e32 v84, 16, v82
	v_and_b32_e32 v85, 0xffff0000, v82
	v_lshlrev_b32_e32 v82, 16, v83
	v_and_b32_e32 v83, 0xffff0000, v83
	v_pk_add_f32 v[82:83], v[74:75], v[82:83]
	v_pk_add_f32 v[84:85], v[72:73], v[84:85]
	v_pk_add_f32 v[76:77], v[76:77], v[88:89]
	s_nop 1
	v_cvt_pk_bf16_f32 v72, v84, v85
	s_nop 1
	v_cvt_pk_bf16_f32 v73, v82, v83
	s_nop 0
	s_nop 1
	v_cvt_pk_bf16_f32 v74, v76, v77
	s_nop 1
	v_cvt_pk_bf16_f32 v75, v78, v79
	global_store_dwordx4 v[86:87], v[72:75], off
	s_nop 1
	v_mul_f32_e32 v72, v85, v85
	v_mul_f32_e32 v73, v83, v83
	v_fmac_f32_e32 v72, v84, v84
	v_fmac_f32_e32 v73, v82, v82
	v_add_f32_e32 v72, v72, v73
	v_mul_f32_e32 v73, v77, v77
	v_mul_f32_e32 v74, v79, v79
	v_fmac_f32_e32 v73, v76, v76
	v_fmac_f32_e32 v74, v78, v78
	v_add_f32_e32 v73, v73, v74
	v_add_f32_e32 v82, v72, v73
	v_mov_b64_e32 v[72:73], v[214:215]
	v_mov_b64_e32 v[74:75], v[216:217]
	v_lshlrev_b32_e32 v76, 16, v72
	v_and_b32_e32 v77, 0xffff0000, v72
	v_lshlrev_b32_e32 v72, 16, v73
	v_and_b32_e32 v73, 0xffff0000, v73
	v_lshlrev_b32_e32 v78, 16, v74
	v_and_b32_e32 v79, 0xffff0000, v74
	v_lshlrev_b32_e32 v74, 16, v75
	v_and_b32_e32 v75, 0xffff0000, v75
	v_pk_add_f32 v[70:71], v[70:71], v[72:73]
	v_pk_add_f32 v[68:69], v[68:69], v[76:77]
	v_pk_add_f32 v[72:73], v[66:67], v[74:75]
	v_pk_add_f32 v[74:75], v[64:65], v[78:79]
	s_nop 1
	v_cvt_pk_bf16_f32 v64, v68, v69
	s_nop 1
	v_cvt_pk_bf16_f32 v65, v70, v71
	s_nop 0
	s_nop 1
	v_cvt_pk_bf16_f32 v66, v74, v75
	s_nop 1
	v_cvt_pk_bf16_f32 v67, v72, v73
	global_store_dwordx4 v[86:87], v[64:67], off offset:256
	s_nop 1
	v_mul_f32_e32 v64, v69, v69
	v_mul_f32_e32 v65, v71, v71
	v_fmac_f32_e32 v64, v68, v68
	v_fmac_f32_e32 v65, v70, v70
	v_add_f32_e32 v64, v64, v65
	v_mul_f32_e32 v65, v75, v75
	v_mul_f32_e32 v66, v73, v73
	v_fmac_f32_e32 v65, v74, v74
	v_fmac_f32_e32 v66, v72, v72
	v_add_f32_e32 v65, v65, v66
	v_and_b32_e32 v66, 64, v164
	v_add_f32_e32 v64, v64, v65
	v_xor_b32_e32 v65, 16, v164
	v_add_u32_e32 v66, 64, v66
	v_cmp_lt_i32_e32 vcc, v65, v66
	v_add_f32_e32 v64, v82, v64
	s_nop 0
	v_cndmask_b32_e32 v65, v164, v65, vcc
	v_lshlrev_b32_e32 v65, 2, v65
	ds_bpermute_b32 v65, v65, v64
	s_waitcnt lgkmcnt(0)
	v_add_f32_e32 v64, v64, v65
	v_xor_b32_e32 v65, 32, v164
	v_cmp_lt_i32_e32 vcc, v65, v66
	s_nop 1
	v_cndmask_b32_e32 v65, v164, v65, vcc
	v_lshlrev_b32_e32 v65, 2, v65
	ds_bpermute_b32 v65, v65, v64
	s_and_b64 exec, exec, s[10:11]
	s_cbranch_execz .LBB0_1070
	s_waitcnt lgkmcnt(0)
	v_add_f32_e32 v66, v64, v65
	v_lshlrev_b64 v[64:65], 7, v[80:81]
	s_lshl_b32 s8, s57, 2
	v_lshl_add_u64 v[64:65], s[26:27], 0, v[64:65]
	s_ashr_i32 s9, s8, 31
	v_lshl_add_u64 v[64:65], s[8:9], 2, v[64:65]
	s_lshl_b32 s8, s82, 2
	s_mov_b32 s9, s3
	v_lshl_add_u64 v[64:65], v[64:65], 0, s[8:9]
	flat_store_dword v[64:65], v66 sc1

.LBB0_1371:
	v_mov_b32_e32 v0, v183
	s_nop 0
	v_ashrrev_i32_e32 v1, 6, v0
	v_cmp_lt_i32_e32 vcc, 1, v1
	s_and_saveexec_b64 s[2:3], vcc
	s_xor_b64 s[2:3], exec, s[2:3]
	s_cbranch_execz .LBB0_1391
	s_mul_i32 s8, s20, 0x180
	s_addk_i32 s8, 0xff80
	v_add_u32_e32 v36, s8, v0
	s_mov_b32 s8, 0x104000
	v_cmp_gt_i32_e32 vcc, s8, v36
	v_lshlrev_b32_e32 v37, 3, v36
	s_mul_i32 s21, s22, 0xc00
	s_and_saveexec_b64 s[10:11], vcc
	s_cbranch_execz .LBB0_1387
	s_add_u32 s8, s0, 0x18cc0000
	s_addc_u32 s9, s1, 0
	s_add_u32 s12, s0, 0x19d40000
	v_readlane_b32 s48, v254, 14
	s_addc_u32 s13, s1, 0
	v_readlane_b32 s49, v254, 15
	v_readlane_b32 s50, v254, 16
	v_readlane_b32 s51, v254, 17
	v_readlane_b32 s52, v254, 18
	v_readlane_b32 s53, v254, 19
	s_add_u32 s14, s0, 0x24240000
	v_readlane_b32 s54, v254, 20
	v_readlane_b32 s55, v254, 21
	v_readlane_b32 s56, v254, 22
	v_readlane_b32 s57, v254, 23
	s_mov_b64 s[48:49], s[52:53]
	s_addc_u32 s15, s1, 0
	s_mov_b64 s[50:51], s[54:55]
	s_mov_b64 s[52:53], s[56:57]
	v_readlane_b32 s58, v254, 24
	v_readlane_b32 s59, v254, 25
	v_readlane_b32 s60, v254, 26
	v_readlane_b32 s61, v254, 27
	v_readlane_b32 s62, v254, 28
	v_readlane_b32 s63, v254, 29
	s_add_u32 s16, s52, 0x100000
	s_addc_u32 s17, s53, 0
	v_readlane_b32 s48, v254, 30
	v_readlane_b32 s52, v254, 34
	v_readlane_b32 s53, v254, 35
	v_readlane_b32 s54, v254, 36
	v_readlane_b32 s55, v254, 37
	s_mov_b64 s[40:41], s[52:53]
	s_mov_b64 s[42:43], s[54:55]
	s_add_u32 s42, s42, 0x3000
	s_addc_u32 s43, s43, 0
	v_readlane_b32 s49, v254, 31
	s_add_u32 s48, s68, 0x4390000
	v_readlane_b32 s50, v254, 32
	s_addc_u32 s49, s69, 0
	v_readlane_b32 s51, v254, 33
	v_readlane_b32 s60, v254, 42
	v_readlane_b32 s61, v254, 43
	v_readlane_b32 s62, v254, 44
	v_readlane_b32 s63, v254, 45
	s_add_u32 s50, s68, 0x4300000
	s_addc_u32 s51, s69, 0
	v_lshlrev_b32_e32 v38, 3, v36
	s_mov_b64 s[60:61], 0
	v_mov_b32_e32 v31, 0
	s_mov_b64 s[62:63], 0x1000
	v_mov_b32_e32 v39, v36
	v_readlane_b32 s56, v254, 38
	v_readlane_b32 s57, v254, 39
	v_readlane_b32 s58, v254, 40
	v_readlane_b32 s59, v254, 41
	v_and_b32_e32 v65, 0x3f8, v38
	v_lshlrev_b32_e32 v64, 1, v65
	v_lshlrev_b32_e32 v65, 2, v65
	s_add_u32 s64, s42, 0x1000
	s_addc_u32 s65, s43, 0
	s_add_u32 s66, s42, 0x2000
	s_addc_u32 s67, s43, 0
	global_load_dwordx4 v[68:71], v65, s[42:43]
	global_load_dwordx4 v[72:75], v65, s[42:43] offset:16
	global_load_dwordx4 v[76:79], v65, s[64:65]
	global_load_dwordx4 v[80:83], v65, s[64:65] offset:16
	global_load_dwordx4 v[84:87], v65, s[66:67]
	global_load_dwordx4 v[88:91], v65, s[66:67] offset:16
	s_waitcnt vmcnt(0)
	s_branch .LBB0_1375

.LBB0_1375:
	v_readfirstlane_b32 s24, v39
	s_nop 0
	s_ashr_i32 s25, s24, 7
	s_cmpk_gt_i32 s25, 0x1fff
	s_cbranch_scc1 .Lconv_slow_L1
	s_and_b32 s76, s25, 0x7ff
	s_add_i32 s76, s76, -2
	s_cmpk_gt_u32 s76, 0x7fb
	s_cbranch_scc1 .Lconv_slow_L1
	s_lshl_b32 s25, s25, 11
	s_add_u32 s64, s12, s25
	s_addc_u32 s65, s13, 0
	s_add_u32 s66, s8, s25
	s_addc_u32 s67, s9, 0
	s_add_u32 s72, s14, s25
	s_addc_u32 s73, s15, 0
	global_load_dwordx4 v[92:95], v64, s[66:67]
	global_load_dwordx4 v[96:99], v64, s[64:65]
	global_load_dwordx4 v[100:103], v64, s[64:65] offset:-2048
	global_load_dwordx4 v[104:107], v64, s[64:65] offset:-4096
	v_add_u32_e32 v39, s94, v39
	v_add_u32_e32 v38, s21, v38
	s_add_i32 s24, s24, s94
	s_waitcnt vmcnt(0)
	v_lshlrev_b32_e32 v116, 16, v100
	v_and_b32_e32 v117, 0xffff0000, v100
	v_lshlrev_b32_e32 v118, 16, v101
	v_and_b32_e32 v119, 0xffff0000, v101
	v_lshlrev_b32_e32 v120, 16, v102
	v_and_b32_e32 v121, 0xffff0000, v102
	v_lshlrev_b32_e32 v122, 16, v103
	v_and_b32_e32 v123, 0xffff0000, v103
	v_lshlrev_b32_e32 v124, 16, v104
	v_and_b32_e32 v125, 0xffff0000, v104
	v_lshlrev_b32_e32 v126, 16, v105
	v_and_b32_e32 v127, 0xffff0000, v105
	v_lshlrev_b32_e32 v128, 16, v106
	v_and_b32_e32 v129, 0xffff0000, v106
	v_lshlrev_b32_e32 v130, 16, v107
	v_and_b32_e32 v131, 0xffff0000, v107
	v_lshlrev_b32_e32 v108, 16, v96
	v_and_b32_e32 v109, 0xffff0000, v96
	v_lshlrev_b32_e32 v110, 16, v97
	v_and_b32_e32 v111, 0xffff0000, v97
	v_lshlrev_b32_e32 v112, 16, v98
	v_and_b32_e32 v113, 0xffff0000, v98
	v_lshlrev_b32_e32 v114, 16, v99
	v_and_b32_e32 v115, 0xffff0000, v99
	v_lshlrev_b32_e32 v132, 16, v92
	v_and_b32_e32 v133, 0xffff0000, v92
	v_lshlrev_b32_e32 v134, 16, v93
	v_and_b32_e32 v135, 0xffff0000, v93
	v_lshlrev_b32_e32 v136, 16, v94
	v_and_b32_e32 v137, 0xffff0000, v94
	v_lshlrev_b32_e32 v138, 16, v95
	v_and_b32_e32 v139, 0xffff0000, v95
	v_pk_mul_f32 v[116:117], v[116:117], v[76:77]
	v_pk_mul_f32 v[118:119], v[118:119], v[78:79]
	v_pk_mul_f32 v[120:121], v[120:121], v[80:81]
	v_pk_mul_f32 v[122:123], v[122:123], v[82:83]
	v_pk_fma_f32 v[116:117], v[124:125], v[68:69], v[116:117]
	v_pk_fma_f32 v[118:119], v[126:127], v[70:71], v[118:119]
	v_pk_fma_f32 v[120:121], v[128:129], v[72:73], v[120:121]
	v_pk_fma_f32 v[122:123], v[130:131], v[74:75], v[122:123]
	v_pk_fma_f32 v[108:109], v[84:85], v[108:109], v[116:117]
	v_pk_fma_f32 v[110:111], v[86:87], v[110:111], v[118:119]
	v_pk_fma_f32 v[112:113], v[88:89], v[112:113], v[120:121]
	v_pk_fma_f32 v[114:115], v[90:91], v[114:115], v[122:123]
	v_pk_mul_f32 v[108:109], v[108:109], v[132:133]
	v_pk_mul_f32 v[110:111], v[110:111], v[134:135]
	v_pk_mul_f32 v[112:113], v[112:113], v[136:137]
	v_pk_mul_f32 v[114:115], v[114:115], v[138:139]
	v_cvt_pk_bf16_f32 v140, v108, v109
	v_cvt_pk_bf16_f32 v141, v110, v111
	v_cvt_pk_bf16_f32 v142, v112, v113
	v_cvt_pk_bf16_f32 v143, v114, v115
	global_store_dwordx4 v64, v[140:143], s[72:73]
	s_cmp_gt_i32 s24, 0x103fff
	s_cbranch_scc0 .LBB0_1375
	s_branch .LBB0_1387

.LBB0_1714:
	s_lshl_b32 s1, s0, 8
	v_or_b32_e32 v152, s1, v160
	s_cmp_gt_i32 s6, -1
	v_ashrrev_i32_e32 v153, 31, v152
	s_cbranch_scc1 .LBB0_1744
	s_lshl_b32 s39, s4, 8
	v_add_u32_e32 v154, s39, v138
	v_lshlrev_b32_e32 v180, 12, v154
	v_mov_b32_e32 v181, 0
	v_lshl_add_u64 v[180:181], s[12:13], 0, v[180:181]
	v_lshl_add_u64 v[180:181], v[152:153], 1, v[180:181]
	global_load_dwordx4 v[184:187], v[180:181], off
	global_load_dwordx4 v[188:191], v[180:181], off offset:256
	v_add_co_u32_e32 v180, vcc, 0x10000, v180
	s_nop 1
	v_addc_co_u32_e32 v181, vcc, 0, v181, vcc
	global_load_dwordx4 v[192:195], v[180:181], off
	global_load_dwordx4 v[196:199], v[180:181], off offset:256
	v_add_co_u32_e32 v180, vcc, 0x10000, v180
	s_nop 1
	v_addc_co_u32_e32 v181, vcc, 0, v181, vcc
	global_load_dwordx4 v[200:203], v[180:181], off
	global_load_dwordx4 v[204:207], v[180:181], off offset:256
	v_add_co_u32_e32 v180, vcc, 0x10000, v180
	s_nop 1
	v_addc_co_u32_e32 v181, vcc, 0, v181, vcc
	global_load_dwordx4 v[208:211], v[180:181], off
	global_load_dwordx4 v[212:215], v[180:181], off offset:256
	s_waitcnt vmcnt(0)
	v_cmp_gt_i32_e32 vcc, s66, v154
	s_and_saveexec_b64 s[8:9], vcc
	s_cbranch_execz .LBB0_1718
	v_ashrrev_i32_e32 v155, 31, v154
	v_lshlrev_b64 v[156:157], 12, v[154:155]
	v_lshl_add_u64 v[156:157], s[12:13], 0, v[156:157]
	v_lshl_add_u64 v[156:157], v[152:153], 1, v[156:157]
	v_mov_b64_e32 v[166:167], v[184:185]
	v_mov_b64_e32 v[168:169], v[186:187]
	v_lshlrev_b32_e32 v170, 16, v166
	v_and_b32_e32 v171, 0xffff0000, v166
	v_lshlrev_b32_e32 v166, 16, v167
	v_and_b32_e32 v167, 0xffff0000, v167
	v_pk_add_f32 v[174:175], v[62:63], v[166:167]
	v_pk_add_f32 v[170:171], v[60:61], v[170:171]
	v_lshlrev_b32_e32 v172, 16, v168
	v_and_b32_e32 v173, 0xffff0000, v168
	v_lshlrev_b32_e32 v168, 16, v169
	v_and_b32_e32 v169, 0xffff0000, v169
	v_mul_f32_e32 v136, v171, v171
	v_mul_f32_e32 v165, v175, v175
	v_pk_add_f32 v[176:177], v[58:59], v[168:169]
	v_pk_add_f32 v[172:173], v[56:57], v[172:173]
	s_nop 1
	v_cvt_pk_bf16_f32 v166, v170, v171
	v_fmac_f32_e32 v136, v170, v170
	v_fmac_f32_e32 v165, v174, v174
	s_nop 1
	v_cvt_pk_bf16_f32 v167, v174, v175
	s_nop 1
	v_cvt_pk_bf16_f32 v168, v172, v173
	s_nop 1
	v_cvt_pk_bf16_f32 v169, v176, v177
	global_store_dwordx4 v[156:157], v[166:169], off
	v_add_f32_e32 v136, v136, v165
	v_mul_f32_e32 v165, v173, v173
	v_mul_f32_e32 v166, v177, v177
	v_fmac_f32_e32 v165, v172, v172
	v_fmac_f32_e32 v166, v176, v176
	v_add_f32_e32 v165, v165, v166
	v_mov_b64_e32 v[166:167], v[188:189]
	v_mov_b64_e32 v[168:169], v[190:191]
	v_add_f32_e32 v136, v136, v165
	v_lshlrev_b32_e32 v170, 16, v166
	v_and_b32_e32 v171, 0xffff0000, v166
	v_lshlrev_b32_e32 v166, 16, v167
	v_and_b32_e32 v167, 0xffff0000, v167
	v_lshlrev_b32_e32 v172, 16, v168
	v_and_b32_e32 v173, 0xffff0000, v168
	v_lshlrev_b32_e32 v168, 16, v169
	v_and_b32_e32 v169, 0xffff0000, v169
	v_pk_add_f32 v[174:175], v[38:39], v[166:167]
	v_pk_add_f32 v[170:171], v[36:37], v[170:171]
	v_pk_add_f32 v[176:177], v[34:35], v[168:169]
	v_pk_add_f32 v[172:173], v[32:33], v[172:173]
	s_nop 1
	v_cvt_pk_bf16_f32 v166, v170, v171
	s_nop 1
	v_cvt_pk_bf16_f32 v167, v174, v175
	v_mul_f32_e32 v165, v177, v177
	s_nop 1
	v_cvt_pk_bf16_f32 v168, v172, v173
	s_nop 1
	v_cvt_pk_bf16_f32 v169, v176, v177
	global_store_dwordx4 v[156:157], v[166:169], off offset:256
	v_mul_f32_e32 v156, v171, v171
	v_mul_f32_e32 v157, v175, v175
	v_fmac_f32_e32 v156, v170, v170
	v_fmac_f32_e32 v157, v174, v174
	v_add_f32_e32 v156, v156, v157
	v_mul_f32_e32 v157, v173, v173
	v_fmac_f32_e32 v157, v172, v172
	v_fmac_f32_e32 v165, v176, v176
	v_add_f32_e32 v157, v157, v165
	v_add_f32_e32 v156, v156, v157
	v_and_b32_e32 v157, 64, v164
	v_add_f32_e32 v136, v136, v156
	v_xor_b32_e32 v156, 16, v164
	v_add_u32_e32 v157, 64, v157
	v_cmp_lt_i32_e32 vcc, v156, v157
	s_nop 1
	v_cndmask_b32_e32 v156, v164, v156, vcc
	v_lshlrev_b32_e32 v156, 2, v156
	ds_bpermute_b32 v156, v156, v136
	s_waitcnt lgkmcnt(0)
	v_add_f32_e32 v136, v136, v156
	v_xor_b32_e32 v156, 32, v164
	v_cmp_lt_i32_e32 vcc, v156, v157
	s_nop 1
	v_cndmask_b32_e32 v156, v164, v156, vcc
	v_lshlrev_b32_e32 v156, 2, v156
	ds_bpermute_b32 v156, v156, v136
	s_and_b64 exec, exec, s[2:3]
	s_cbranch_execz .LBB0_1718
	s_waitcnt lgkmcnt(0)
	v_add_f32_e32 v136, v136, v156
	v_lshlrev_b64 v[156:157], 7, v[154:155]
	s_lshl_b32 s48, s0, 2
	v_lshl_add_u64 v[156:157], s[16:17], 0, v[156:157]
	s_ashr_i32 s49, s48, 31
	v_lshl_add_u64 v[156:157], s[48:49], 2, v[156:157]
	s_lshl_b32 s48, s61, 2
	s_mov_b32 s49, s7
	v_lshl_add_u64 v[156:157], v[156:157], 0, s[48:49]
	flat_store_dword v[156:157], v136 sc1
.LBB0_1718:
	s_or_b64 exec, exec, s[8:9]
	s_waitcnt lgkmcnt(0)
	v_or_b32_e32 v156, 16, v154
	v_cmp_gt_i32_e32 vcc, s66, v156
	s_and_saveexec_b64 s[8:9], vcc
	s_cbranch_execz .LBB0_1721
	v_ashrrev_i32_e32 v157, 31, v156
	v_lshlrev_b64 v[166:167], 12, v[156:157]
	v_lshl_add_u64 v[166:167], s[12:13], 0, v[166:167]
	v_lshl_add_u64 v[170:171], v[152:153], 1, v[166:167]
	v_mov_b64_e32 v[166:167], v[192:193]
	v_mov_b64_e32 v[168:169], v[194:195]
	v_lshlrev_b32_e32 v172, 16, v168
	v_and_b32_e32 v173, 0xffff0000, v168
	v_lshlrev_b32_e32 v168, 16, v169
	v_and_b32_e32 v169, 0xffff0000, v169
	v_pk_add_f32 v[174:175], v[50:51], v[168:169]
	v_lshlrev_b32_e32 v168, 16, v166
	v_and_b32_e32 v169, 0xffff0000, v166
	v_lshlrev_b32_e32 v166, 16, v167
	v_and_b32_e32 v167, 0xffff0000, v167
	v_pk_add_f32 v[172:173], v[48:49], v[172:173]
	v_pk_add_f32 v[176:177], v[54:55], v[166:167]
	v_pk_add_f32 v[178:179], v[52:53], v[168:169]
	v_mul_f32_e32 v155, v177, v177
	s_nop 1
	v_cvt_pk_bf16_f32 v166, v178, v179
	s_nop 1
	v_cvt_pk_bf16_f32 v167, v176, v177
	s_nop 1
	v_cvt_pk_bf16_f32 v168, v172, v173
	s_nop 1
	v_cvt_pk_bf16_f32 v169, v174, v175
	global_store_dwordx4 v[170:171], v[166:169], off
	s_nop 1
	v_mov_b64_e32 v[166:167], v[196:197]
	v_mov_b64_e32 v[168:169], v[198:199]
	v_mul_f32_e32 v136, v179, v179
	v_fmac_f32_e32 v136, v178, v178
	v_fmac_f32_e32 v155, v176, v176
	v_add_f32_e32 v136, v136, v155
	v_mul_f32_e32 v155, v173, v173
	v_mul_f32_e32 v165, v175, v175
	v_fmac_f32_e32 v155, v172, v172
	v_fmac_f32_e32 v165, v174, v174
	v_add_f32_e32 v155, v155, v165
	v_add_f32_e32 v136, v136, v155
	v_lshlrev_b32_e32 v172, 16, v166
	v_and_b32_e32 v173, 0xffff0000, v166
	v_lshlrev_b32_e32 v166, 16, v167
	v_and_b32_e32 v167, 0xffff0000, v167
	v_pk_add_f32 v[176:177], v[22:23], v[166:167]
	v_pk_add_f32 v[172:173], v[20:21], v[172:173]
	v_lshlrev_b32_e32 v174, 16, v168
	v_and_b32_e32 v175, 0xffff0000, v168
	v_lshlrev_b32_e32 v168, 16, v169
	v_and_b32_e32 v169, 0xffff0000, v169
	v_mul_f32_e32 v155, v173, v173
	v_mul_f32_e32 v165, v177, v177
	v_pk_add_f32 v[178:179], v[18:19], v[168:169]
	v_pk_add_f32 v[174:175], v[16:17], v[174:175]
	s_nop 1
	v_cvt_pk_bf16_f32 v166, v172, v173
	v_fmac_f32_e32 v155, v172, v172
	v_fmac_f32_e32 v165, v176, v176
	s_nop 1
	v_cvt_pk_bf16_f32 v167, v176, v177
	s_nop 1
	v_cvt_pk_bf16_f32 v168, v174, v175
	s_nop 1
	v_cvt_pk_bf16_f32 v169, v178, v179
	global_store_dwordx4 v[170:171], v[166:169], off offset:256
	v_add_f32_e32 v155, v155, v165
	v_mul_f32_e32 v165, v175, v175
	v_mul_f32_e32 v166, v179, v179
	v_fmac_f32_e32 v165, v174, v174
	v_fmac_f32_e32 v166, v178, v178
	v_add_f32_e32 v165, v165, v166
	v_add_f32_e32 v155, v155, v165
	v_and_b32_e32 v165, 64, v164
	v_add_f32_e32 v136, v136, v155
	v_xor_b32_e32 v155, 16, v164
	v_add_u32_e32 v165, 64, v165
	v_cmp_lt_i32_e32 vcc, v155, v165
	s_nop 1
	v_cndmask_b32_e32 v155, v164, v155, vcc
	v_lshlrev_b32_e32 v155, 2, v155
	ds_bpermute_b32 v155, v155, v136
	s_waitcnt lgkmcnt(0)
	v_add_f32_e32 v136, v136, v155
	v_xor_b32_e32 v155, 32, v164
	v_cmp_lt_i32_e32 vcc, v155, v165
	s_nop 1
	v_cndmask_b32_e32 v155, v164, v155, vcc
	v_lshlrev_b32_e32 v155, 2, v155
	ds_bpermute_b32 v155, v155, v136
	s_and_b64 exec, exec, s[2:3]
	s_cbranch_execz .LBB0_1721
	v_lshlrev_b64 v[156:157], 7, v[156:157]
	s_lshl_b32 s48, s0, 2
	v_lshl_add_u64 v[156:157], s[16:17], 0, v[156:157]
	s_ashr_i32 s49, s48, 31
	v_lshl_add_u64 v[156:157], s[48:49], 2, v[156:157]
	s_lshl_b32 s48, s61, 2
	s_mov_b32 s49, s7
	s_waitcnt lgkmcnt(0)
	v_add_f32_e32 v136, v136, v155
	v_lshl_add_u64 v[156:157], v[156:157], 0, s[48:49]
	flat_store_dword v[156:157], v136 sc1
.LBB0_1721:
	s_or_b64 exec, exec, s[8:9]
	v_or_b32_e32 v156, 32, v154
	v_cmp_gt_i32_e32 vcc, s66, v156
	s_and_saveexec_b64 s[8:9], vcc
	s_cbranch_execz .LBB0_1724
	v_ashrrev_i32_e32 v157, 31, v156
	v_lshlrev_b64 v[166:167], 12, v[156:157]
	v_lshl_add_u64 v[166:167], s[12:13], 0, v[166:167]
	v_lshl_add_u64 v[170:171], v[152:153], 1, v[166:167]
	v_mov_b64_e32 v[166:167], v[200:201]
	v_mov_b64_e32 v[168:169], v[202:203]
	v_lshlrev_b32_e32 v172, 16, v168
	v_and_b32_e32 v173, 0xffff0000, v168
	v_lshlrev_b32_e32 v168, 16, v169
	v_and_b32_e32 v169, 0xffff0000, v169
	v_pk_add_f32 v[174:175], v[42:43], v[168:169]
	v_lshlrev_b32_e32 v168, 16, v166
	v_and_b32_e32 v169, 0xffff0000, v166
	v_lshlrev_b32_e32 v166, 16, v167
	v_and_b32_e32 v167, 0xffff0000, v167
	v_pk_add_f32 v[172:173], v[40:41], v[172:173]
	v_pk_add_f32 v[176:177], v[46:47], v[166:167]
	v_pk_add_f32 v[178:179], v[44:45], v[168:169]
	s_waitcnt lgkmcnt(0)
	v_mul_f32_e32 v155, v177, v177
	s_nop 1
	v_cvt_pk_bf16_f32 v166, v178, v179
	s_nop 1
	v_cvt_pk_bf16_f32 v167, v176, v177
	s_nop 1
	v_cvt_pk_bf16_f32 v168, v172, v173
	s_nop 1
	v_cvt_pk_bf16_f32 v169, v174, v175
	global_store_dwordx4 v[170:171], v[166:169], off
	s_nop 1
	v_mov_b64_e32 v[166:167], v[204:205]
	v_mov_b64_e32 v[168:169], v[206:207]
	v_mul_f32_e32 v136, v179, v179
	v_fmac_f32_e32 v136, v178, v178
	v_fmac_f32_e32 v155, v176, v176
	v_add_f32_e32 v136, v136, v155
	v_mul_f32_e32 v155, v173, v173
	v_mul_f32_e32 v165, v175, v175
	v_fmac_f32_e32 v155, v172, v172
	v_fmac_f32_e32 v165, v174, v174
	v_add_f32_e32 v155, v155, v165
	v_add_f32_e32 v136, v136, v155
	v_lshlrev_b32_e32 v172, 16, v166
	v_and_b32_e32 v173, 0xffff0000, v166
	v_lshlrev_b32_e32 v166, 16, v167
	v_and_b32_e32 v167, 0xffff0000, v167
	v_pk_add_f32 v[176:177], v[14:15], v[166:167]
	v_pk_add_f32 v[172:173], v[12:13], v[172:173]
	v_lshlrev_b32_e32 v174, 16, v168
	v_and_b32_e32 v175, 0xffff0000, v168
	v_lshlrev_b32_e32 v168, 16, v169
	v_and_b32_e32 v169, 0xffff0000, v169
	v_mul_f32_e32 v155, v173, v173
	v_mul_f32_e32 v165, v177, v177
	v_pk_add_f32 v[178:179], v[10:11], v[168:169]
	v_pk_add_f32 v[174:175], v[8:9], v[174:175]
	s_nop 1
	v_cvt_pk_bf16_f32 v166, v172, v173
	v_fmac_f32_e32 v155, v172, v172
	v_fmac_f32_e32 v165, v176, v176
	s_nop 1
	v_cvt_pk_bf16_f32 v167, v176, v177
	s_nop 1
	v_cvt_pk_bf16_f32 v168, v174, v175
	s_nop 1
	v_cvt_pk_bf16_f32 v169, v178, v179
	global_store_dwordx4 v[170:171], v[166:169], off offset:256
	v_add_f32_e32 v155, v155, v165
	v_mul_f32_e32 v165, v175, v175
	v_mul_f32_e32 v166, v179, v179
	v_fmac_f32_e32 v165, v174, v174
	v_fmac_f32_e32 v166, v178, v178
	v_add_f32_e32 v165, v165, v166
	v_add_f32_e32 v155, v155, v165
	v_and_b32_e32 v165, 64, v164
	v_add_f32_e32 v136, v136, v155
	v_xor_b32_e32 v155, 16, v164
	v_add_u32_e32 v165, 64, v165
	v_cmp_lt_i32_e32 vcc, v155, v165
	s_nop 1
	v_cndmask_b32_e32 v155, v164, v155, vcc
	v_lshlrev_b32_e32 v155, 2, v155
	ds_bpermute_b32 v155, v155, v136
	s_waitcnt lgkmcnt(0)
	v_add_f32_e32 v136, v136, v155
	v_xor_b32_e32 v155, 32, v164
	v_cmp_lt_i32_e32 vcc, v155, v165
	s_nop 1
	v_cndmask_b32_e32 v155, v164, v155, vcc
	v_lshlrev_b32_e32 v155, 2, v155
	ds_bpermute_b32 v155, v155, v136
	s_and_b64 exec, exec, s[2:3]
	s_cbranch_execz .LBB0_1724
	v_lshlrev_b64 v[156:157], 7, v[156:157]
	s_lshl_b32 s48, s0, 2
	v_lshl_add_u64 v[156:157], s[16:17], 0, v[156:157]
	s_ashr_i32 s49, s48, 31
	v_lshl_add_u64 v[156:157], s[48:49], 2, v[156:157]
	s_lshl_b32 s48, s61, 2
	s_mov_b32 s49, s7
	s_waitcnt lgkmcnt(0)
	v_add_f32_e32 v136, v136, v155
	v_lshl_add_u64 v[156:157], v[156:157], 0, s[48:49]
	flat_store_dword v[156:157], v136 sc1
.LBB0_1724:
	s_or_b64 exec, exec, s[8:9]
	v_or_b32_e32 v156, 48, v154
	v_cmp_gt_i32_e32 vcc, s66, v156
	s_and_saveexec_b64 s[8:9], vcc
	s_cbranch_execz .LBB0_1727
	v_ashrrev_i32_e32 v157, 31, v156
	v_lshlrev_b64 v[166:167], 12, v[156:157]
	v_lshl_add_u64 v[166:167], s[12:13], 0, v[166:167]
	v_lshl_add_u64 v[170:171], v[152:153], 1, v[166:167]
	v_mov_b64_e32 v[166:167], v[208:209]
	v_mov_b64_e32 v[168:169], v[210:211]
	v_lshlrev_b32_e32 v172, 16, v168
	v_and_b32_e32 v173, 0xffff0000, v168
	v_lshlrev_b32_e32 v168, 16, v169
	v_and_b32_e32 v169, 0xffff0000, v169
	v_pk_add_f32 v[174:175], v[26:27], v[168:169]
	v_lshlrev_b32_e32 v168, 16, v166
	v_and_b32_e32 v169, 0xffff0000, v166
	v_lshlrev_b32_e32 v166, 16, v167
	v_and_b32_e32 v167, 0xffff0000, v167
	v_pk_add_f32 v[172:173], v[24:25], v[172:173]
	v_pk_add_f32 v[176:177], v[30:31], v[166:167]
	v_pk_add_f32 v[178:179], v[28:29], v[168:169]
	s_waitcnt lgkmcnt(0)
	v_mul_f32_e32 v155, v177, v177
	s_nop 1
	v_cvt_pk_bf16_f32 v166, v178, v179
	s_nop 1
	v_cvt_pk_bf16_f32 v167, v176, v177
	s_nop 1
	v_cvt_pk_bf16_f32 v168, v172, v173
	s_nop 1
	v_cvt_pk_bf16_f32 v169, v174, v175
	global_store_dwordx4 v[170:171], v[166:169], off
	s_nop 1
	v_mov_b64_e32 v[166:167], v[212:213]
	v_mov_b64_e32 v[168:169], v[214:215]
	v_mul_f32_e32 v136, v179, v179
	v_fmac_f32_e32 v136, v178, v178
	v_fmac_f32_e32 v155, v176, v176
	v_add_f32_e32 v136, v136, v155
	v_mul_f32_e32 v155, v173, v173
	v_mul_f32_e32 v165, v175, v175
	v_fmac_f32_e32 v155, v172, v172
	v_fmac_f32_e32 v165, v174, v174
	v_add_f32_e32 v155, v155, v165
	v_add_f32_e32 v136, v136, v155
	v_lshlrev_b32_e32 v172, 16, v166
	v_and_b32_e32 v173, 0xffff0000, v166
	v_lshlrev_b32_e32 v166, 16, v167
	v_and_b32_e32 v167, 0xffff0000, v167
	v_pk_add_f32 v[176:177], v[6:7], v[166:167]
	v_pk_add_f32 v[172:173], v[4:5], v[172:173]
	v_lshlrev_b32_e32 v174, 16, v168
	v_and_b32_e32 v175, 0xffff0000, v168
	v_lshlrev_b32_e32 v168, 16, v169
	v_and_b32_e32 v169, 0xffff0000, v169
	v_mul_f32_e32 v155, v173, v173
	v_mul_f32_e32 v165, v177, v177
	v_pk_add_f32 v[178:179], v[2:3], v[168:169]
	v_pk_add_f32 v[174:175], v[0:1], v[174:175]
	s_nop 1
	v_cvt_pk_bf16_f32 v166, v172, v173
	v_fmac_f32_e32 v155, v172, v172
	v_fmac_f32_e32 v165, v176, v176
	s_nop 1
	v_cvt_pk_bf16_f32 v167, v176, v177
	s_nop 1
	v_cvt_pk_bf16_f32 v168, v174, v175
	s_nop 1
	v_cvt_pk_bf16_f32 v169, v178, v179
	global_store_dwordx4 v[170:171], v[166:169], off offset:256
	v_add_f32_e32 v155, v155, v165
	v_mul_f32_e32 v165, v175, v175
	v_mul_f32_e32 v166, v179, v179
	v_fmac_f32_e32 v165, v174, v174
	v_fmac_f32_e32 v166, v178, v178
	v_add_f32_e32 v165, v165, v166
	v_add_f32_e32 v155, v155, v165
	v_and_b32_e32 v165, 64, v164
	v_add_f32_e32 v136, v136, v155
	v_xor_b32_e32 v155, 16, v164
	v_add_u32_e32 v165, 64, v165
	v_cmp_lt_i32_e32 vcc, v155, v165
	s_nop 1
	v_cndmask_b32_e32 v155, v164, v155, vcc
	v_lshlrev_b32_e32 v155, 2, v155
	ds_bpermute_b32 v155, v155, v136
	s_waitcnt lgkmcnt(0)
	v_add_f32_e32 v136, v136, v155
	v_xor_b32_e32 v155, 32, v164
	v_cmp_lt_i32_e32 vcc, v155, v165
	s_nop 1
	v_cndmask_b32_e32 v155, v164, v155, vcc
	v_lshlrev_b32_e32 v155, 2, v155
	ds_bpermute_b32 v155, v155, v136
	s_and_b64 exec, exec, s[2:3]
	s_cbranch_execz .LBB0_1727
	v_lshlrev_b64 v[156:157], 7, v[156:157]
	s_lshl_b32 s48, s0, 2
	v_lshl_add_u64 v[156:157], s[16:17], 0, v[156:157]
	s_ashr_i32 s49, s48, 31
	v_lshl_add_u64 v[156:157], s[48:49], 2, v[156:157]
	s_lshl_b32 s48, s61, 2
	s_mov_b32 s49, s7
	s_waitcnt lgkmcnt(0)
	v_add_f32_e32 v136, v136, v155
	v_lshl_add_u64 v[156:157], v[156:157], 0, s[48:49]
	flat_store_dword v[156:157], v136 sc1
.LBB0_1727:
	s_or_b64 exec, exec, s[8:9]
	s_movk_i32 s5, 0x2080
	v_lshlrev_b32_e32 v180, 12, v154
	v_mov_b32_e32 v181, 0
	v_lshl_add_u64 v[180:181], s[12:13], 0, v[180:181]
	v_lshl_add_u64 v[180:181], v[152:153], 1, v[180:181]
	v_add_co_u32_e32 v180, vcc, 0x80000, v180
	s_nop 1
	v_addc_co_u32_e32 v181, vcc, 0, v181, vcc
	global_load_dwordx4 v[184:187], v[180:181], off
	global_load_dwordx4 v[188:191], v[180:181], off offset:256
	v_add_co_u32_e32 v180, vcc, 0x10000, v180
	s_nop 1
	v_addc_co_u32_e32 v181, vcc, 0, v181, vcc
	global_load_dwordx4 v[192:195], v[180:181], off
	global_load_dwordx4 v[196:199], v[180:181], off offset:256
	v_add_co_u32_e32 v180, vcc, 0x10000, v180
	s_nop 1
	v_addc_co_u32_e32 v181, vcc, 0, v181, vcc
	global_load_dwordx4 v[200:203], v[180:181], off
	global_load_dwordx4 v[204:207], v[180:181], off offset:256
	v_add_co_u32_e32 v180, vcc, 0x10000, v180
	s_nop 1
	v_addc_co_u32_e32 v181, vcc, 0, v181, vcc
	global_load_dwordx4 v[208:211], v[180:181], off
	global_load_dwordx4 v[212:215], v[180:181], off offset:256
	s_waitcnt vmcnt(0)
	v_cmp_gt_i32_e32 vcc, s5, v154
	s_and_saveexec_b64 s[8:9], vcc
	s_cbranch_execz .LBB0_1730
	v_add_u32_e32 v156, 0x80, v154
	v_ashrrev_i32_e32 v157, 31, v156
	v_lshlrev_b64 v[166:167], 12, v[156:157]
	v_lshl_add_u64 v[166:167], s[12:13], 0, v[166:167]
	v_lshl_add_u64 v[170:171], v[152:153], 1, v[166:167]
	v_mov_b64_e32 v[166:167], v[184:185]
	v_mov_b64_e32 v[168:169], v[186:187]
	v_lshlrev_b32_e32 v172, 16, v168
	v_and_b32_e32 v173, 0xffff0000, v168
	v_lshlrev_b32_e32 v168, 16, v169
	v_and_b32_e32 v169, 0xffff0000, v169
	v_pk_add_f32 v[126:127], v[126:127], v[168:169]
	v_lshlrev_b32_e32 v168, 16, v166
	v_and_b32_e32 v169, 0xffff0000, v166
	v_lshlrev_b32_e32 v166, 16, v167
	v_and_b32_e32 v167, 0xffff0000, v167
	v_pk_add_f32 v[166:167], v[122:123], v[166:167]
	v_pk_add_f32 v[168:169], v[120:121], v[168:169]
	v_pk_add_f32 v[124:125], v[124:125], v[172:173]
	s_nop 1
	v_cvt_pk_bf16_f32 v120, v168, v169
	s_nop 1
	v_cvt_pk_bf16_f32 v121, v166, v167
	s_nop 0
	s_nop 1
	v_cvt_pk_bf16_f32 v122, v124, v125
	s_nop 1
	v_cvt_pk_bf16_f32 v123, v126, v127
	global_store_dwordx4 v[170:171], v[120:123], off
	s_nop 1
	v_mul_f32_e32 v120, v169, v169
	v_mul_f32_e32 v121, v167, v167
	v_fmac_f32_e32 v120, v168, v168
	v_fmac_f32_e32 v121, v166, v166
	v_add_f32_e32 v120, v120, v121
	v_mul_f32_e32 v121, v125, v125
	v_mul_f32_e32 v122, v127, v127
	v_fmac_f32_e32 v121, v124, v124
	v_fmac_f32_e32 v122, v126, v126
	v_add_f32_e32 v121, v121, v122
	v_add_f32_e32 v136, v120, v121
	v_mov_b64_e32 v[120:121], v[188:189]
	v_mov_b64_e32 v[122:123], v[190:191]
	v_lshlrev_b32_e32 v124, 16, v120
	v_and_b32_e32 v125, 0xffff0000, v120
	v_lshlrev_b32_e32 v120, 16, v121
	v_and_b32_e32 v121, 0xffff0000, v121
	v_lshlrev_b32_e32 v126, 16, v122
	v_and_b32_e32 v127, 0xffff0000, v122
	v_lshlrev_b32_e32 v122, 16, v123
	v_and_b32_e32 v123, 0xffff0000, v123
	v_pk_add_f32 v[118:119], v[118:119], v[120:121]
	v_pk_add_f32 v[116:117], v[116:117], v[124:125]
	v_pk_add_f32 v[120:121], v[114:115], v[122:123]
	v_pk_add_f32 v[122:123], v[112:113], v[126:127]
	s_nop 1
	v_cvt_pk_bf16_f32 v112, v116, v117
	s_nop 1
	v_cvt_pk_bf16_f32 v113, v118, v119
	s_nop 0
	s_nop 1
	v_cvt_pk_bf16_f32 v114, v122, v123
	s_nop 1
	v_cvt_pk_bf16_f32 v115, v120, v121
	global_store_dwordx4 v[170:171], v[112:115], off offset:256
	s_nop 1
	v_mul_f32_e32 v112, v117, v117
	v_mul_f32_e32 v113, v119, v119
	v_fmac_f32_e32 v112, v116, v116
	v_fmac_f32_e32 v113, v118, v118
	v_add_f32_e32 v112, v112, v113
	v_mul_f32_e32 v113, v123, v123
	v_mul_f32_e32 v114, v121, v121
	v_fmac_f32_e32 v113, v122, v122
	v_fmac_f32_e32 v114, v120, v120
	v_add_f32_e32 v113, v113, v114
	v_and_b32_e32 v114, 64, v164
	v_add_f32_e32 v112, v112, v113
	v_xor_b32_e32 v113, 16, v164
	v_add_u32_e32 v114, 64, v114
	v_cmp_lt_i32_e32 vcc, v113, v114
	v_add_f32_e32 v112, v136, v112
	s_nop 0
	v_cndmask_b32_e32 v113, v164, v113, vcc
	v_lshlrev_b32_e32 v113, 2, v113
	ds_bpermute_b32 v113, v113, v112
	s_waitcnt lgkmcnt(0)
	v_add_f32_e32 v112, v112, v113
	v_xor_b32_e32 v113, 32, v164
	v_cmp_lt_i32_e32 vcc, v113, v114
	s_nop 1
	v_cndmask_b32_e32 v113, v164, v113, vcc
	v_lshlrev_b32_e32 v113, 2, v113
	ds_bpermute_b32 v113, v113, v112
	s_and_b64 exec, exec, s[2:3]
	s_cbranch_execz .LBB0_1730
	s_waitcnt lgkmcnt(0)
	v_add_f32_e32 v114, v112, v113
	v_lshlrev_b64 v[112:113], 7, v[156:157]
	s_lshl_b32 s48, s0, 2
	v_lshl_add_u64 v[112:113], s[16:17], 0, v[112:113]
	s_ashr_i32 s49, s48, 31
	v_lshl_add_u64 v[112:113], s[48:49], 2, v[112:113]
	s_lshl_b32 s48, s61, 2
	s_mov_b32 s49, s7
	v_lshl_add_u64 v[112:113], v[112:113], 0, s[48:49]
	flat_store_dword v[112:113], v114 sc1
.LBB0_1730:
	s_or_b64 exec, exec, s[8:9]
	s_movk_i32 s5, 0x2070
	v_cmp_gt_i32_e32 vcc, s5, v154
	s_and_saveexec_b64 s[8:9], vcc
	s_cbranch_execz .LBB0_1733
	v_add_u32_e32 v112, 0x90, v154
	s_waitcnt lgkmcnt(0)
	v_ashrrev_i32_e32 v113, 31, v112
	v_lshlrev_b64 v[114:115], 12, v[112:113]
	v_lshl_add_u64 v[114:115], s[12:13], 0, v[114:115]
	v_lshl_add_u64 v[118:119], v[152:153], 1, v[114:115]
	v_mov_b64_e32 v[114:115], v[192:193]
	v_mov_b64_e32 v[116:117], v[194:195]
	v_lshlrev_b32_e32 v120, 16, v116
	v_and_b32_e32 v121, 0xffff0000, v116
	v_lshlrev_b32_e32 v116, 16, v117
	v_and_b32_e32 v117, 0xffff0000, v117
	v_pk_add_f32 v[110:111], v[110:111], v[116:117]
	v_lshlrev_b32_e32 v116, 16, v114
	v_and_b32_e32 v117, 0xffff0000, v114
	v_lshlrev_b32_e32 v114, 16, v115
	v_and_b32_e32 v115, 0xffff0000, v115
	v_pk_add_f32 v[114:115], v[106:107], v[114:115]
	v_pk_add_f32 v[116:117], v[104:105], v[116:117]
	v_pk_add_f32 v[108:109], v[108:109], v[120:121]
	s_nop 1
	v_cvt_pk_bf16_f32 v104, v116, v117
	s_nop 1
	v_cvt_pk_bf16_f32 v105, v114, v115
	s_nop 0
	s_nop 1
	v_cvt_pk_bf16_f32 v106, v108, v109
	s_nop 1
	v_cvt_pk_bf16_f32 v107, v110, v111
	global_store_dwordx4 v[118:119], v[104:107], off
	s_nop 1
	v_mul_f32_e32 v104, v117, v117
	v_mul_f32_e32 v105, v115, v115
	v_fmac_f32_e32 v104, v116, v116
	v_fmac_f32_e32 v105, v114, v114
	v_add_f32_e32 v104, v104, v105
	v_mul_f32_e32 v105, v109, v109
	v_mul_f32_e32 v106, v111, v111
	v_fmac_f32_e32 v105, v108, v108
	v_fmac_f32_e32 v106, v110, v110
	v_add_f32_e32 v105, v105, v106
	v_add_f32_e32 v114, v104, v105
	v_mov_b64_e32 v[104:105], v[196:197]
	v_mov_b64_e32 v[106:107], v[198:199]
	v_lshlrev_b32_e32 v108, 16, v104
	v_and_b32_e32 v109, 0xffff0000, v104
	v_lshlrev_b32_e32 v104, 16, v105
	v_and_b32_e32 v105, 0xffff0000, v105
	v_lshlrev_b32_e32 v110, 16, v106
	v_and_b32_e32 v111, 0xffff0000, v106
	v_lshlrev_b32_e32 v106, 16, v107
	v_and_b32_e32 v107, 0xffff0000, v107
	v_pk_add_f32 v[102:103], v[102:103], v[104:105]
	v_pk_add_f32 v[100:101], v[100:101], v[108:109]
	v_pk_add_f32 v[104:105], v[98:99], v[106:107]
	v_pk_add_f32 v[106:107], v[96:97], v[110:111]
	s_nop 1
	v_cvt_pk_bf16_f32 v96, v100, v101
	s_nop 1
	v_cvt_pk_bf16_f32 v97, v102, v103
	s_nop 0
	s_nop 1
	v_cvt_pk_bf16_f32 v98, v106, v107
	s_nop 1
	v_cvt_pk_bf16_f32 v99, v104, v105
	global_store_dwordx4 v[118:119], v[96:99], off offset:256
	s_nop 1
	v_mul_f32_e32 v96, v101, v101
	v_mul_f32_e32 v97, v103, v103
	v_fmac_f32_e32 v96, v100, v100
	v_fmac_f32_e32 v97, v102, v102
	v_add_f32_e32 v96, v96, v97
	v_mul_f32_e32 v97, v107, v107
	v_mul_f32_e32 v98, v105, v105
	v_fmac_f32_e32 v97, v106, v106
	v_fmac_f32_e32 v98, v104, v104
	v_add_f32_e32 v97, v97, v98
	v_and_b32_e32 v98, 64, v164
	v_add_f32_e32 v96, v96, v97
	v_xor_b32_e32 v97, 16, v164
	v_add_u32_e32 v98, 64, v98
	v_cmp_lt_i32_e32 vcc, v97, v98
	v_add_f32_e32 v96, v114, v96
	s_nop 0
	v_cndmask_b32_e32 v97, v164, v97, vcc
	v_lshlrev_b32_e32 v97, 2, v97
	ds_bpermute_b32 v97, v97, v96
	s_waitcnt lgkmcnt(0)
	v_add_f32_e32 v96, v96, v97
	v_xor_b32_e32 v97, 32, v164
	v_cmp_lt_i32_e32 vcc, v97, v98
	s_nop 1
	v_cndmask_b32_e32 v97, v164, v97, vcc
	v_lshlrev_b32_e32 v97, 2, v97
	ds_bpermute_b32 v97, v97, v96
	s_and_b64 exec, exec, s[2:3]
	s_cbranch_execz .LBB0_1733
	s_waitcnt lgkmcnt(0)
	v_add_f32_e32 v98, v96, v97
	v_lshlrev_b64 v[96:97], 7, v[112:113]
	s_lshl_b32 s48, s0, 2
	v_lshl_add_u64 v[96:97], s[16:17], 0, v[96:97]
	s_ashr_i32 s49, s48, 31
	v_lshl_add_u64 v[96:97], s[48:49], 2, v[96:97]
	s_lshl_b32 s48, s61, 2
	s_mov_b32 s49, s7
	v_lshl_add_u64 v[96:97], v[96:97], 0, s[48:49]
	flat_store_dword v[96:97], v98 sc1
.LBB0_1733:
	s_or_b64 exec, exec, s[8:9]
	s_movk_i32 s5, 0x2060
	v_cmp_gt_i32_e32 vcc, s5, v154
	s_and_saveexec_b64 s[8:9], vcc
	s_cbranch_execz .LBB0_1736
	v_add_u32_e32 v96, 0xa0, v154
	s_waitcnt lgkmcnt(0)
	v_ashrrev_i32_e32 v97, 31, v96
	v_lshlrev_b64 v[98:99], 12, v[96:97]
	v_lshl_add_u64 v[98:99], s[12:13], 0, v[98:99]
	v_lshl_add_u64 v[102:103], v[152:153], 1, v[98:99]
	v_mov_b64_e32 v[98:99], v[200:201]
	v_mov_b64_e32 v[100:101], v[202:203]
	v_lshlrev_b32_e32 v104, 16, v100
	v_and_b32_e32 v105, 0xffff0000, v100
	v_lshlrev_b32_e32 v100, 16, v101
	v_and_b32_e32 v101, 0xffff0000, v101
	v_pk_add_f32 v[94:95], v[94:95], v[100:101]
	v_lshlrev_b32_e32 v100, 16, v98
	v_and_b32_e32 v101, 0xffff0000, v98
	v_lshlrev_b32_e32 v98, 16, v99
	v_and_b32_e32 v99, 0xffff0000, v99
	v_pk_add_f32 v[98:99], v[90:91], v[98:99]
	v_pk_add_f32 v[100:101], v[88:89], v[100:101]
	v_pk_add_f32 v[92:93], v[92:93], v[104:105]
	s_nop 1
	v_cvt_pk_bf16_f32 v88, v100, v101
	s_nop 1
	v_cvt_pk_bf16_f32 v89, v98, v99
	s_nop 0
	s_nop 1
	v_cvt_pk_bf16_f32 v90, v92, v93
	s_nop 1
	v_cvt_pk_bf16_f32 v91, v94, v95
	global_store_dwordx4 v[102:103], v[88:91], off
	s_nop 1
	v_mul_f32_e32 v88, v101, v101
	v_mul_f32_e32 v89, v99, v99
	v_fmac_f32_e32 v88, v100, v100
	v_fmac_f32_e32 v89, v98, v98
	v_add_f32_e32 v88, v88, v89
	v_mul_f32_e32 v89, v93, v93
	v_mul_f32_e32 v90, v95, v95
	v_fmac_f32_e32 v89, v92, v92
	v_fmac_f32_e32 v90, v94, v94
	v_add_f32_e32 v89, v89, v90
	v_add_f32_e32 v98, v88, v89
	v_mov_b64_e32 v[88:89], v[204:205]
	v_mov_b64_e32 v[90:91], v[206:207]
	v_lshlrev_b32_e32 v92, 16, v88
	v_and_b32_e32 v93, 0xffff0000, v88
	v_lshlrev_b32_e32 v88, 16, v89
	v_and_b32_e32 v89, 0xffff0000, v89
	v_lshlrev_b32_e32 v94, 16, v90
	v_and_b32_e32 v95, 0xffff0000, v90
	v_lshlrev_b32_e32 v90, 16, v91
	v_and_b32_e32 v91, 0xffff0000, v91
	v_pk_add_f32 v[86:87], v[86:87], v[88:89]
	v_pk_add_f32 v[84:85], v[84:85], v[92:93]
	v_pk_add_f32 v[88:89], v[82:83], v[90:91]
	v_pk_add_f32 v[90:91], v[80:81], v[94:95]
	s_nop 1
	v_cvt_pk_bf16_f32 v80, v84, v85
	s_nop 1
	v_cvt_pk_bf16_f32 v81, v86, v87
	s_nop 0
	s_nop 1
	v_cvt_pk_bf16_f32 v82, v90, v91
	s_nop 1
	v_cvt_pk_bf16_f32 v83, v88, v89
	global_store_dwordx4 v[102:103], v[80:83], off offset:256
	s_nop 1
	v_mul_f32_e32 v80, v85, v85
	v_mul_f32_e32 v81, v87, v87
	v_fmac_f32_e32 v80, v84, v84
	v_fmac_f32_e32 v81, v86, v86
	v_add_f32_e32 v80, v80, v81
	v_mul_f32_e32 v81, v91, v91
	v_mul_f32_e32 v82, v89, v89
	v_fmac_f32_e32 v81, v90, v90
	v_fmac_f32_e32 v82, v88, v88
	v_add_f32_e32 v81, v81, v82
	v_and_b32_e32 v82, 64, v164
	v_add_f32_e32 v80, v80, v81
	v_xor_b32_e32 v81, 16, v164
	v_add_u32_e32 v82, 64, v82
	v_cmp_lt_i32_e32 vcc, v81, v82
	v_add_f32_e32 v80, v98, v80
	s_nop 0
	v_cndmask_b32_e32 v81, v164, v81, vcc
	v_lshlrev_b32_e32 v81, 2, v81
	ds_bpermute_b32 v81, v81, v80
	s_waitcnt lgkmcnt(0)
	v_add_f32_e32 v80, v80, v81
	v_xor_b32_e32 v81, 32, v164
	v_cmp_lt_i32_e32 vcc, v81, v82
	s_nop 1
	v_cndmask_b32_e32 v81, v164, v81, vcc
	v_lshlrev_b32_e32 v81, 2, v81
	ds_bpermute_b32 v81, v81, v80
	s_and_b64 exec, exec, s[2:3]
	s_cbranch_execz .LBB0_1736
	s_waitcnt lgkmcnt(0)
	v_add_f32_e32 v82, v80, v81
	v_lshlrev_b64 v[80:81], 7, v[96:97]
	s_lshl_b32 s48, s0, 2
	v_lshl_add_u64 v[80:81], s[16:17], 0, v[80:81]
	s_ashr_i32 s49, s48, 31
	v_lshl_add_u64 v[80:81], s[48:49], 2, v[80:81]
	s_lshl_b32 s48, s61, 2
	s_mov_b32 s49, s7
	v_lshl_add_u64 v[80:81], v[80:81], 0, s[48:49]
	flat_store_dword v[80:81], v82 sc1
.LBB0_1736:
	s_or_b64 exec, exec, s[8:9]
	s_movk_i32 s5, 0x2050
	v_cmp_gt_i32_e32 vcc, s5, v154
	s_and_saveexec_b64 s[8:9], vcc
	s_cbranch_execz .LBB0_1739
	v_add_u32_e32 v80, 0xb0, v154
	s_waitcnt lgkmcnt(0)
	v_ashrrev_i32_e32 v81, 31, v80
	v_lshlrev_b64 v[82:83], 12, v[80:81]
	v_lshl_add_u64 v[82:83], s[12:13], 0, v[82:83]
	v_lshl_add_u64 v[86:87], v[152:153], 1, v[82:83]
	v_mov_b64_e32 v[82:83], v[208:209]
	v_mov_b64_e32 v[84:85], v[210:211]
	v_lshlrev_b32_e32 v88, 16, v84
	v_and_b32_e32 v89, 0xffff0000, v84
	v_lshlrev_b32_e32 v84, 16, v85
	v_and_b32_e32 v85, 0xffff0000, v85
	v_pk_add_f32 v[78:79], v[78:79], v[84:85]
	v_lshlrev_b32_e32 v84, 16, v82
	v_and_b32_e32 v85, 0xffff0000, v82
	v_lshlrev_b32_e32 v82, 16, v83
	v_and_b32_e32 v83, 0xffff0000, v83
	v_pk_add_f32 v[82:83], v[74:75], v[82:83]
	v_pk_add_f32 v[84:85], v[72:73], v[84:85]
	v_pk_add_f32 v[76:77], v[76:77], v[88:89]
	s_nop 1
	v_cvt_pk_bf16_f32 v72, v84, v85
	s_nop 1
	v_cvt_pk_bf16_f32 v73, v82, v83
	s_nop 0
	s_nop 1
	v_cvt_pk_bf16_f32 v74, v76, v77
	s_nop 1
	v_cvt_pk_bf16_f32 v75, v78, v79
	global_store_dwordx4 v[86:87], v[72:75], off
	s_nop 1
	v_mul_f32_e32 v72, v85, v85
	v_mul_f32_e32 v73, v83, v83
	v_fmac_f32_e32 v72, v84, v84
	v_fmac_f32_e32 v73, v82, v82
	v_add_f32_e32 v72, v72, v73
	v_mul_f32_e32 v73, v77, v77
	v_mul_f32_e32 v74, v79, v79
	v_fmac_f32_e32 v73, v76, v76
	v_fmac_f32_e32 v74, v78, v78
	v_add_f32_e32 v73, v73, v74
	v_add_f32_e32 v82, v72, v73
	v_mov_b64_e32 v[72:73], v[212:213]
	v_mov_b64_e32 v[74:75], v[214:215]
	v_lshlrev_b32_e32 v76, 16, v72
	v_and_b32_e32 v77, 0xffff0000, v72
	v_lshlrev_b32_e32 v72, 16, v73
	v_and_b32_e32 v73, 0xffff0000, v73
	v_lshlrev_b32_e32 v78, 16, v74
	v_and_b32_e32 v79, 0xffff0000, v74
	v_lshlrev_b32_e32 v74, 16, v75
	v_and_b32_e32 v75, 0xffff0000, v75
	v_pk_add_f32 v[70:71], v[70:71], v[72:73]
	v_pk_add_f32 v[68:69], v[68:69], v[76:77]
	v_pk_add_f32 v[72:73], v[66:67], v[74:75]
	v_pk_add_f32 v[74:75], v[64:65], v[78:79]
	s_nop 1
	v_cvt_pk_bf16_f32 v64, v68, v69
	s_nop 1
	v_cvt_pk_bf16_f32 v65, v70, v71
	s_nop 0
	s_nop 1
	v_cvt_pk_bf16_f32 v66, v74, v75
	s_nop 1
	v_cvt_pk_bf16_f32 v67, v72, v73
	global_store_dwordx4 v[86:87], v[64:67], off offset:256
	s_nop 1
	v_mul_f32_e32 v64, v69, v69
	v_mul_f32_e32 v65, v71, v71
	v_fmac_f32_e32 v64, v68, v68
	v_fmac_f32_e32 v65, v70, v70
	v_add_f32_e32 v64, v64, v65
	v_mul_f32_e32 v65, v75, v75
	v_mul_f32_e32 v66, v73, v73
	v_fmac_f32_e32 v65, v74, v74
	v_fmac_f32_e32 v66, v72, v72
	v_add_f32_e32 v65, v65, v66
	v_and_b32_e32 v66, 64, v164
	v_add_f32_e32 v64, v64, v65
	v_xor_b32_e32 v65, 16, v164
	v_add_u32_e32 v66, 64, v66
	v_cmp_lt_i32_e32 vcc, v65, v66
	v_add_f32_e32 v64, v82, v64
	s_nop 0
	v_cndmask_b32_e32 v65, v164, v65, vcc
	v_lshlrev_b32_e32 v65, 2, v65
	ds_bpermute_b32 v65, v65, v64
	s_waitcnt lgkmcnt(0)
	v_add_f32_e32 v64, v64, v65
	v_xor_b32_e32 v65, 32, v164
	v_cmp_lt_i32_e32 vcc, v65, v66
	s_nop 1
	v_cndmask_b32_e32 v65, v164, v65, vcc
	v_lshlrev_b32_e32 v65, 2, v65
	ds_bpermute_b32 v65, v65, v64
	s_and_b64 exec, exec, s[2:3]
	s_cbranch_execz .LBB0_1739
	s_waitcnt lgkmcnt(0)
	v_add_f32_e32 v66, v64, v65
	v_lshlrev_b64 v[64:65], 7, v[80:81]
	s_lshl_b32 s48, s0, 2
	v_lshl_add_u64 v[64:65], s[16:17], 0, v[64:65]
	s_ashr_i32 s49, s48, 31
	v_lshl_add_u64 v[64:65], s[48:49], 2, v[64:65]
	s_lshl_b32 s48, s61, 2
	s_mov_b32 s49, s7
	v_lshl_add_u64 v[64:65], v[64:65], 0, s[48:49]
	flat_store_dword v[64:65], v66 sc1
